# compressed-branch gate load issued at the start of each quad instead of right before its use
# speedup vs baseline: 1.0006x; 1.0006x over previous
; #define LAS __attribute__((address_space(3)))
; __device__ __forceinline__ void nsa_quad_pre(int bg, int quad, const bf16_t* Q, const bf16_t* KV, const bf16_t* KCMP, const bf16_t* VCMPT, const float* GN, bf16_t* ONSA, ...
;     const int r16 = lane & 15, q4 = lane >> 4, b = bg >> 2, g = bg & 3, t0 = quad * 4;
;     const unsigned koff = (unsigned)(r16 * 64 + q4 * 8) * 2u, voffS = (unsigned)(r16 * SEQ + q4 * 8) * 2u, voffC = (unsigned)(r16 * 512 + q4 * 8) * 2u;
;     const char* KWb = (const char*)(KV + 4 * (size_t)MTOK * 256 + (size_t)bg * SEQ * 64); const char* VWb = (const char*)(KV + 5 * (size_t)MTOK * 256 + (size_t)bg * 64 * SEQ);
;     const char* KCb = (const char*)(KCMP + (size_t)bg * 512 * 64); const char* VCb = (const char*)(VCMPT + (size_t)bg * 64 * 512);
;     ...
;     const size_t qoff = (size_t)(b * SEQ + t0 + (r16 & 3)) * 1024 + (g * 4 + (r16 >> 2)) * 64 + q4 * 8;
;     { const bf16x8 a0 = *(const bf16x8*)(Q + qoff), a1 = *(const bf16x8*)(Q + qoff + 32); *(LAS bf16x8*)(qfw + lane * 8) = a0; *(LAS bf16x8*)(qfw + 512 + lane * 8) = a1; }
;     const LAS bf16_t* qf = qfw + lane * 8;
;     const LAS float* bt = btab + q4 * 1028;
;     const f32x4 z4 = {0.f, 0.f, 0.f, 0.f};
;     KFrag KF; VFrag VF; f32x4 sc[4];
;     const int w_lo = (t0 - 511 > 0 ? t0 - 511 : 0) >> 6, w_hi = t0 >> 6;
;     f32x4 oc[4] = {z4, z4, z4, z4};
;     const int tl = t0 + 3, nvmax = tl >= 31 ? ((tl - 31) >> 4) + 1 : 0, ngr = (nvmax + 63) >> 6;
;     if (ngr > 0) {
;     ...
;     for (int tt = 0; tt < 4; ++tt) { const float gc = GN[(size_t)(b * SEQ + t0 + tt) * 48 + (g * 4 + q4) * 3];
.LBB0_738:
	s_lshl_b32 s1, s3, 5
	s_sub_i32 s14, s1, s91
	s_and_b32 s0, s3, 1
	s_add_i32 s14, s14, 31
	s_add_i32 s1, s1, s91
	s_cmp_eq_u32 s0, 0
	s_cselect_b32 s18, s1, s14
	v_and_b32_e32 v232, 15, v184
	v_lshrrev_b32_e32 v233, 4, v184
	v_and_b32_e32 v234, 3, v232
	v_lshrrev_b32_e32 v235, 2, v232
	v_mul_u32_u24_e32 v173, 0x1010, v235
	ds_read_b32 v225, v173 offset:4096
	v_mov_b32_e32 v252, 0xf149f2ca
	v_and_b32_e32 v253, 1, v235
	v_xor_b32_e32 v0, v233, v234
	v_lshlrev_b32_e32 v0, 4, v0
	v_lshl_add_u32 v0, v253, 6, v0
	v_lshl_add_u32 v98, v235, 3, v234
	v_lshl_add_u32 v176, v98, 7, v0
	s_lshl_b32 s33, s80, 7
	v_lshl_add_u32 v177, v232, 7, v0
	v_subrev_u32_e32 v177, s33, v177
	v_lshlrev_b32_e32 v98, 7, v253
	v_sub_u32_e32 v178, 64, v98
	v_lshrrev_b32_e32 v98, 3, v184
	v_and_b32_e32 v99, 7, v184
	s_lshr_b32 s0, s80, 3
	s_and_b32 s1, s0, 1
	s_lshl_b32 s1, s1, 2
	v_and_b32_e32 v253, 3, v98
	v_or_b32_e32 v253, s1, v253
	v_xor_b32_e32 v253, v99, v253
	v_add_u32_e32 v0, s80, v98
	v_lshlrev_b32_e32 v174, 7, v0
	v_lshl_add_u32 v174, v253, 4, v174
	v_xor_b32_e32 v253, v99, v98
	v_lshlrev_b32_e32 v175, 10, v0
	v_lshl_add_u32 v175, v253, 4, v175
	s_add_i32 s94, s33, 0xa040
	s_add_i32 s95, s33, 0x1dc40
	s_add_i32 s46, s33, 0x20200
	s_lshr_b32 s15, s97, 13
	s_lshl_b32 s15, s15, 2
	s_and_b32 s1, s88, 3
	s_or_b32 s15, s15, s1
	s_lshl_b32 s15, s15, 16
	s_add_u32 s68, s30, 0x38110000
	s_addc_u32 s69, s31, 0
	s_add_u32 s68, s68, s15
	s_addc_u32 s69, s69, 0
	s_add_u32 s70, s30, 0x38210000
	s_addc_u32 s71, s31, 0
	s_add_u32 s70, s70, s15
	s_addc_u32 s71, s71, 0
	s_lshl_b32 s74, s18, 2
	s_add_i32 s74, s74, 66
	s_lshr_b32 s74, s74, 6
	s_mov_b32 s75, 0
	s_mov_b32 s92, 0
	s_mov_b32 s93, 0
	s_lshl_b32 s0, s92, 13
	s_add_i32 s0, s0, s33
	s_add_i32 m0, s0, 16448
	s_lshl_b32 s1, s93, 13
	s_add_u32 s72, s68, s1
	s_addc_u32 s73, s69, 0
	global_load_lds_dwordx4 v174, s[72:73]
	s_cmp_eq_u32 s92, 1
	s_cselect_b32 s0, s95, s94
	s_cmp_eq_u32 s92, 2
	s_cselect_b32 m0, s46, s0
	s_lshl_b32 s1, s93, 7
	s_add_u32 s72, s70, s1
	s_addc_u32 s73, s71, 0
	global_load_lds_dwordx4 v175, s[72:73]
	s_add_i32 s93, s93, 1
	s_cmp_ge_i32 s93, s74
	s_cselect_b32 s93, 0, s93
	s_add_i32 s92, s92, 1
	s_cmp_eq_u32 s92, 3
	s_cselect_b32 s92, 0, s92
	s_lshl_b32 s0, s92, 13
	s_add_i32 s0, s0, s33
	s_add_i32 m0, s0, 16448
	s_lshl_b32 s1, s93, 13
	s_add_u32 s72, s68, s1
	s_addc_u32 s73, s69, 0
	global_load_lds_dwordx4 v174, s[72:73]
	s_cmp_eq_u32 s92, 1
	s_cselect_b32 s0, s95, s94
	s_cmp_eq_u32 s92, 2
	s_cselect_b32 m0, s46, s0
	s_lshl_b32 s1, s93, 7
	s_add_u32 s72, s70, s1
	s_addc_u32 s73, s71, 0
	global_load_lds_dwordx4 v175, s[72:73]
	s_add_i32 s93, s93, 1
	s_cmp_ge_i32 s93, s74
	s_cselect_b32 s93, 0, s93
	s_add_i32 s92, s92, 1
	s_cmp_eq_u32 s92, 3
	s_cselect_b32 s92, 0, s92
	v_lshlrev_b32_e32 v98, 7, v233
	v_sub_u32_e32 v172, v234, v98
	v_add_u32_e32 v172, 0xffffffe1, v172
	s_lshl_b32 s0, s80, 10
	s_add_i32 s0, s0, 56384
	v_lshlrev_b32_e32 v215, 11, v234
	v_lshl_add_u32 v215, v233, 5, v215
	v_add_u32_e32 v215, s0, v215
	s_lshl_b32 s0, s18, 6
	s_add_i32 s0, s0, s97
	s_add_i32 s0, s0, s80
	v_add_u32_e32 v253, s0, v234
	s_and_b32 s1, s88, 3
	s_lshl_b32 s1, s1, 2
	v_add_u32_e32 v98, s1, v235
	v_lshlrev_b32_e32 v98, 7, v98
	v_lshl_add_u32 v98, v253, 11, v98
	v_lshl_add_u32 v98, v233, 4, v98
	v_add_u32_e32 v99, 0x2000, v98
	s_add_u32 s72, s30, 0x29900000
	s_addc_u32 s73, s31, 0
	global_load_dwordx4 v[34:37], v98, s[72:73] offset:0
	global_load_dwordx4 v[38:41], v98, s[72:73] offset:64
	global_load_dwordx4 v[42:45], v99, s[72:73] offset:0
	global_load_dwordx4 v[46:49], v99, s[72:73] offset:64
	s_waitcnt lgkmcnt(0)
	s_lshl_b32 s47, s18, 6
	s_add_i32 s47, s47, s80
	v_and_b32_e32 v232, 15, v184
	v_and_b32_e32 v234, 3, v232
	v_lshrrev_b32_e32 v235, 2, v232
	s_add_i32 s0, s47, s97
	v_add_u32_e32 v253, s0, v234
	s_and_b32 s1, s88, 3
	s_lshl_b32 s1, s1, 2
	v_add_u32_e32 v0, s1, v235
	v_mul_u32_u24_e32 v99, 0xc0, v253
	v_mul_u32_u24_e32 v0, 12, v0
	v_add_u32_e32 v99, v99, v0
	s_add_u32 s72, s30, 0x38310000
	s_addc_u32 s73, s31, 0
	global_load_dword v227, v99, s[72:73]
	v_mov_b32_e32 v2, 0
	v_mov_b32_e32 v3, 0
	v_mov_b32_e32 v4, 0
	v_mov_b32_e32 v5, 0
	v_mov_b32_e32 v6, 0
	v_mov_b32_e32 v7, 0
	v_mov_b32_e32 v8, 0
	v_mov_b32_e32 v9, 0
	v_mov_b32_e32 v10, 0
	v_mov_b32_e32 v11, 0
	v_mov_b32_e32 v12, 0
	v_mov_b32_e32 v13, 0
	v_mov_b32_e32 v14, 0
	v_mov_b32_e32 v15, 0
	v_mov_b32_e32 v16, 0
	v_mov_b32_e32 v17, 0
	s_sub_i32 s0, s47, 28
	s_ashr_i32 s0, s0, 4
	s_add_i32 s0, s0, 64
	s_ashr_i32 s53, s0, 6
	s_cmp_gt_i32 s47, 27
	s_cselect_b32 s53, s53, 0
	s_sub_i32 s0, s47, 2063
	s_ashr_i32 s52, s0, 10
	s_add_i32 s52, s52, 1
	s_max_i32 s52, s52, 0
	s_min_i32 s52, s52, s53
	v_add_u32_e32 v99, s47, v172
	v_and_b32_e32 v98, 15, v184
	v_mov_b32_e32 v170, 0
	s_waitcnt vmcnt(0)
	s_barrier
	s_mov_b32 s57, 0

; #define LAS __attribute__((address_space(3)))
; __device__ __forceinline__ bf16_t tobf(float x) { return (bf16_t)pk2(x, 0.f); }
; __device__ __forceinline__ void nsa_quad_pre(int bg, int quad, const bf16_t* Q, const bf16_t* KV, const bf16_t* KCMP, const bf16_t* VCMPT, const float* GN, bf16_t* ONSA, ...
;     ...
;         for (int gr = 0; gr < ngr; ++gr) {
;             const bool more = gr + 1 < ngr;
;             qk_scores(KF, qf, sc);
;             if (more) load_k(KF, KP_C(gr + 1));
;             cmp_sm2(sc, gr, t0, bt, inv, Pb, psum, r16, q4);
;             pv_step(VF, oc, Pb, r16, q4);
;             if (more) load_v(VF, VP_C(gr + 1));
;         }
;     ...
;             unsigned k0 = 0u, k1 = 0u;
;             { const int j = lane; if (j >= 1 && j <= cur - 2) { const LAS float* ps = psum + tt * 512 + 4 * j - 1; const float v = ps[0] + ps[1] + ps[2] + ps[3] + ps[4]; k0 = (__builtin_bit_cast(unsigned, v) & ~127u) | (unsigned)(127 - j); } }
;             { const int j = lane + 64; if (j <= cur - 2) { const LAS float* ps = psum + tt * 512 + 4 * j - 1; const float v = ps[0] + ps[1] + ps[2] + ps[3] + ps[4]; k1 = (__builtin_bit_cast(unsigned, v) & ~127u) | (unsigned)(127 - j); } }
;             for (int it = 0; it < 13; ++it) {
;                 unsigned m = k0 > k1 ? k0 : k1;
; #pragma unroll
;                 for (int off = 32; off >= 1; off >>= 1) { const unsigned o = (unsigned)__shfl_xor((int)m, off); m = o > m ? o : m; }
;                 if (k0 == m) k0 = 0u; if (k1 == m) k1 = 0u;
;     ...
;     for (int tt = 0; tt < 4; ++tt) { const float gc = GN[(size_t)(b * SEQ + t0 + tt) * 48 + (g * 4 + q4) * 3];
;         bf16_t* op = ONSA + (size_t)(b * SEQ + t0 + tt) * 1024 + (g * 4 + q4) * 64 + r16;
; #pragma unroll
;         for (int nt = 0; nt < 4; ++nt) op[nt * 16] = tobf(gc * oc[nt][tt]); }
.Lcmp_tail_q0p2:
	s_waitcnt vmcnt(2) lgkmcnt(0)
	s_barrier
	s_add_i32 s75, s75, 1
	s_cmp_eq_u32 s75, 3
	s_cselect_b32 s75, 0, s75
	s_add_i32 s57, s57, 1
	s_cmp_lt_i32 s57, s74
	s_cbranch_scc1 .Lcmp_top_q0p2
	s_waitcnt lgkmcnt(0)
	s_nop 7
	s_nop 3
	v_and_b32_e32 v232, 15, v184
	v_lshrrev_b32_e32 v233, 4, v184
	v_and_b32_e32 v234, 3, v232
	v_lshrrev_b32_e32 v235, 2, v232
	s_add_i32 s0, s47, s97
	v_add_u32_e32 v253, s0, v234
	s_and_b32 s1, s88, 3
	s_lshl_b32 s1, s1, 2
	v_add_u32_e32 v0, s1, v235
	v_lshlrev_b32_e32 v98, 7, v0
	v_lshl_add_u32 v98, v253, 11, v98
	v_lshl_add_u32 v98, v233, 3, v98
	s_add_u32 s14, s30, 0xf900000
	s_addc_u32 s15, s31, 0
	s_waitcnt vmcnt(0)
	v_mul_f32_e32 v2, v2, v227
	v_mul_f32_e32 v3, v3, v227
	v_mul_f32_e32 v4, v4, v227
	v_mul_f32_e32 v5, v5, v227
	v_mul_f32_e32 v6, v6, v227
	v_mul_f32_e32 v7, v7, v227
	v_mul_f32_e32 v8, v8, v227
	v_mul_f32_e32 v9, v9, v227
	v_mul_f32_e32 v10, v10, v227
	v_mul_f32_e32 v11, v11, v227
	v_mul_f32_e32 v12, v12, v227
	v_mul_f32_e32 v13, v13, v227
	v_mul_f32_e32 v14, v14, v227
	v_mul_f32_e32 v15, v15, v227
	v_mul_f32_e32 v16, v16, v227
	v_mul_f32_e32 v17, v17, v227
	v_cvt_pk_bf16_f32 v216, v2, v3
	v_cvt_pk_bf16_f32 v217, v4, v5
	v_cvt_pk_bf16_f32 v218, v6, v7
	v_cvt_pk_bf16_f32 v219, v8, v9
	v_cvt_pk_bf16_f32 v220, v10, v11
	v_cvt_pk_bf16_f32 v221, v12, v13
	v_cvt_pk_bf16_f32 v222, v14, v15
	v_cvt_pk_bf16_f32 v223, v16, v17
	global_store_dwordx2 v98, v[216:217], s[14:15] offset:0
	global_store_dwordx2 v98, v[218:219], s[14:15] offset:32
	global_store_dwordx2 v98, v[220:221], s[14:15] offset:64
	global_store_dwordx2 v98, v[222:223], s[14:15] offset:96
	s_waitcnt lgkmcnt(0)
	s_cmp_gt_i32 s18, 15
	s_cbranch_scc0 .Ltopk_small_q0
	s_lshl_b32 s19, s80, 10
	s_add_i32 s19, s19, 56384
	v_lshlrev_b32_e32 v96, 4, v184
	v_add_u32_e32 v96, s19, v96
	v_add_u32_e32 v97, 0xfffffffc, v96
	v_sub_u32_e32 v94, 127, v184
	v_sub_u32_e32 v95, 63, v184
	s_mov_b32 s54, 0xffffff80
	s_add_i32 s21, s18, -2
	v_add_u32_e32 v236, 64, v184
	ds_read_b32 v86, v97 offset:0
	ds_read_b128 v[50:53], v96 offset:0
	ds_read_b32 v87, v97 offset:1024
	ds_read_b128 v[54:57], v96 offset:1024
	ds_read_b32 v88, v97 offset:2048
	ds_read_b128 v[58:61], v96 offset:2048
	ds_read_b32 v89, v97 offset:3072
	ds_read_b128 v[62:65], v96 offset:3072
	s_waitcnt lgkmcnt(6)
	v_add_f32_e32 v86, v86, v50
	v_add_f32_e32 v86, v86, v51
	v_add_f32_e32 v86, v86, v52
	v_add_f32_e32 v86, v86, v53
	v_and_or_b32 v18, v86, s54, v94
	s_waitcnt lgkmcnt(4)
	v_add_f32_e32 v87, v87, v54
	v_add_f32_e32 v87, v87, v55
	v_add_f32_e32 v87, v87, v56
	v_add_f32_e32 v87, v87, v57
	v_and_or_b32 v22, v87, s54, v95
	s_waitcnt lgkmcnt(2)
	v_add_f32_e32 v88, v88, v58
	v_add_f32_e32 v88, v88, v59
	v_add_f32_e32 v88, v88, v60
	v_add_f32_e32 v88, v88, v61
	v_and_or_b32 v19, v88, s54, v94
	s_waitcnt lgkmcnt(0)
	v_add_f32_e32 v89, v89, v62
	v_add_f32_e32 v89, v89, v63
	v_add_f32_e32 v89, v89, v64
	v_add_f32_e32 v89, v89, v65
	v_and_or_b32 v23, v89, s54, v95
	ds_read_b32 v90, v97 offset:4096
	ds_read_b128 v[66:69], v96 offset:4096
	ds_read_b32 v91, v97 offset:5120
	ds_read_b128 v[70:73], v96 offset:5120
	ds_read_b32 v92, v97 offset:6144
	ds_read_b128 v[74:77], v96 offset:6144
	ds_read_b32 v93, v97 offset:7168
	ds_read_b128 v[78:81], v96 offset:7168
	s_waitcnt lgkmcnt(6)
	v_add_f32_e32 v90, v90, v66
	v_add_f32_e32 v90, v90, v67
	v_add_f32_e32 v90, v90, v68
	v_add_f32_e32 v90, v90, v69
	v_and_or_b32 v20, v90, s54, v94
	s_waitcnt lgkmcnt(4)
	v_add_f32_e32 v91, v91, v70
	v_add_f32_e32 v91, v91, v71
	v_add_f32_e32 v91, v91, v72
	v_add_f32_e32 v91, v91, v73
	v_and_or_b32 v24, v91, s54, v95
	s_waitcnt lgkmcnt(2)
	v_add_f32_e32 v92, v92, v74
	v_add_f32_e32 v92, v92, v75
	v_add_f32_e32 v92, v92, v76
	v_add_f32_e32 v92, v92, v77
	v_and_or_b32 v21, v92, s54, v94
	s_waitcnt lgkmcnt(0)
	v_add_f32_e32 v93, v93, v78
	v_add_f32_e32 v93, v93, v79
	v_add_f32_e32 v93, v93, v80
	v_add_f32_e32 v93, v93, v81
	v_and_or_b32 v25, v93, s54, v95
	v_cmp_le_i32_e64 s[14:15], v184, s21
	v_cmp_lt_i32_e64 s[34:35], 0, v184
	s_nop 0
	s_and_b64 s[14:15], s[14:15], s[34:35]
	v_cmp_le_i32_e64 s[34:35], v236, s21
	v_cndmask_b32_e64 v18, 0, v18, s[14:15]
	s_nop 0
	v_cndmask_b32_e64 v22, 0, v22, s[34:35]
	v_mov_b32_e32 v82, 127
	v_cndmask_b32_e64 v19, 0, v19, s[14:15]
	v_cndmask_b32_e64 v23, 0, v23, s[34:35]
	v_mov_b32_e32 v83, 127
	v_cndmask_b32_e64 v20, 0, v20, s[14:15]
	v_cndmask_b32_e64 v24, 0, v24, s[34:35]
	v_mov_b32_e32 v84, 127
	v_cndmask_b32_e64 v21, 0, v21, s[14:15]
	v_cndmask_b32_e64 v25, 0, v25, s[34:35]
	v_mov_b32_e32 v85, 127
	v_max_u32_e32 v26, v18, v22
	v_max_u32_e32 v27, v19, v23
	v_max_u32_e32 v28, v20, v24
	v_max_u32_e32 v29, v21, v25
	v_max_u32_dpp v26, v26, v26 quad_perm:[1,0,3,2] row_mask:0xf bank_mask:0xf
	v_max_u32_dpp v27, v27, v27 quad_perm:[1,0,3,2] row_mask:0xf bank_mask:0xf
	v_max_u32_dpp v28, v28, v28 quad_perm:[1,0,3,2] row_mask:0xf bank_mask:0xf
	v_max_u32_dpp v29, v29, v29 quad_perm:[1,0,3,2] row_mask:0xf bank_mask:0xf
	v_max_u32_dpp v26, v26, v26 quad_perm:[2,3,0,1] row_mask:0xf bank_mask:0xf
	v_max_u32_dpp v27, v27, v27 quad_perm:[2,3,0,1] row_mask:0xf bank_mask:0xf
	v_max_u32_dpp v28, v28, v28 quad_perm:[2,3,0,1] row_mask:0xf bank_mask:0xf
	v_max_u32_dpp v29, v29, v29 quad_perm:[2,3,0,1] row_mask:0xf bank_mask:0xf
	v_max_u32_dpp v26, v26, v26 row_half_mirror row_mask:0xf bank_mask:0xf
	v_max_u32_dpp v27, v27, v27 row_half_mirror row_mask:0xf bank_mask:0xf
	v_max_u32_dpp v28, v28, v28 row_half_mirror row_mask:0xf bank_mask:0xf
	v_max_u32_dpp v29, v29, v29 row_half_mirror row_mask:0xf bank_mask:0xf
	v_max_u32_dpp v26, v26, v26 row_mirror row_mask:0xf bank_mask:0xf
; __device__ __forceinline__ void nsa_quad_pre(int bg, int quad, const bf16_t* Q, const bf16_t* KV, const bf16_t* KCMP, const bf16_t* VCMPT, const float* GN, bf16_t* ONSA, ...
;     ...
;             for (int it = 0; it < 13; ++it) {
;                 unsigned m = k0 > k1 ? k0 : k1;
; #pragma unroll
;                 for (int off = 32; off >= 1; off >>= 1) { const unsigned o = (unsigned)__shfl_xor((int)m, off); m = o > m ? o : m; }
;                 if (k0 == m) k0 = 0u; if (k1 == m) k1 = 0u;
;                 if (lane == 0) selq[tt * 16 + it] = 127 - (int)(m & 127u);
	v_max_u32_dpp v27, v27, v27 row_mirror row_mask:0xf bank_mask:0xf
	v_max_u32_dpp v28, v28, v28 row_mirror row_mask:0xf bank_mask:0xf
	v_max_u32_dpp v29, v29, v29 row_mirror row_mask:0xf bank_mask:0xf
	v_max_u32_dpp v26, v26, v26 row_bcast:15 row_mask:0xa bank_mask:0xf
	v_max_u32_dpp v27, v27, v27 row_bcast:15 row_mask:0xa bank_mask:0xf
	v_max_u32_dpp v28, v28, v28 row_bcast:15 row_mask:0xa bank_mask:0xf
	v_max_u32_dpp v29, v29, v29 row_bcast:15 row_mask:0xa bank_mask:0xf
	v_max_u32_dpp v26, v26, v26 row_bcast:31 row_mask:0xc bank_mask:0xf
	v_max_u32_dpp v27, v27, v27 row_bcast:31 row_mask:0xc bank_mask:0xf
	v_max_u32_dpp v28, v28, v28 row_bcast:31 row_mask:0xc bank_mask:0xf
	v_max_u32_dpp v29, v29, v29 row_bcast:31 row_mask:0xc bank_mask:0xf
	v_readlane_b32 s14, v26, 63
	v_readlane_b32 s15, v27, 63
	v_readlane_b32 s34, v28, 63
	v_readlane_b32 s35, v29, 63
	v_writelane_b32 v82, s14, 0
	v_writelane_b32 v83, s15, 0
	v_writelane_b32 v84, s34, 0
	v_writelane_b32 v85, s35, 0
	v_cmp_ne_u32_e64 s[42:43], s14, v18
	v_cmp_ne_u32_e64 s[66:67], s14, v22
	v_cmp_ne_u32_e64 s[0:1], s15, v19
	v_cmp_ne_u32_e32 vcc, s15, v23
	v_cndmask_b32_e64 v18, 0, v18, s[42:43]
	v_cndmask_b32_e64 v22, 0, v22, s[66:67]
	v_cndmask_b32_e64 v19, 0, v19, s[0:1]
	v_cndmask_b32_e32 v23, 0, v23, vcc
	v_cmp_ne_u32_e64 s[42:43], s34, v20
	v_cmp_ne_u32_e64 s[66:67], s34, v24
	v_cmp_ne_u32_e64 s[0:1], s35, v21
	v_cmp_ne_u32_e32 vcc, s35, v25
	v_cndmask_b32_e64 v20, 0, v20, s[42:43]
	v_cndmask_b32_e64 v24, 0, v24, s[66:67]
	v_cndmask_b32_e64 v21, 0, v21, s[0:1]
	v_cndmask_b32_e32 v25, 0, v25, vcc
	v_max_u32_e32 v26, v18, v22
	v_max_u32_e32 v27, v19, v23
	v_max_u32_e32 v28, v20, v24
	v_max_u32_e32 v29, v21, v25
	v_max_u32_dpp v26, v26, v26 quad_perm:[1,0,3,2] row_mask:0xf bank_mask:0xf
	v_max_u32_dpp v27, v27, v27 quad_perm:[1,0,3,2] row_mask:0xf bank_mask:0xf
	v_max_u32_dpp v28, v28, v28 quad_perm:[1,0,3,2] row_mask:0xf bank_mask:0xf
	v_max_u32_dpp v29, v29, v29 quad_perm:[1,0,3,2] row_mask:0xf bank_mask:0xf
	v_max_u32_dpp v26, v26, v26 quad_perm:[2,3,0,1] row_mask:0xf bank_mask:0xf
	v_max_u32_dpp v27, v27, v27 quad_perm:[2,3,0,1] row_mask:0xf bank_mask:0xf
	v_max_u32_dpp v28, v28, v28 quad_perm:[2,3,0,1] row_mask:0xf bank_mask:0xf
	v_max_u32_dpp v29, v29, v29 quad_perm:[2,3,0,1] row_mask:0xf bank_mask:0xf
	v_max_u32_dpp v26, v26, v26 row_half_mirror row_mask:0xf bank_mask:0xf
	v_max_u32_dpp v27, v27, v27 row_half_mirror row_mask:0xf bank_mask:0xf
	v_max_u32_dpp v28, v28, v28 row_half_mirror row_mask:0xf bank_mask:0xf
	v_max_u32_dpp v29, v29, v29 row_half_mirror row_mask:0xf bank_mask:0xf
	v_max_u32_dpp v26, v26, v26 row_mirror row_mask:0xf bank_mask:0xf
	v_max_u32_dpp v27, v27, v27 row_mirror row_mask:0xf bank_mask:0xf
	v_max_u32_dpp v28, v28, v28 row_mirror row_mask:0xf bank_mask:0xf
	v_max_u32_dpp v29, v29, v29 row_mirror row_mask:0xf bank_mask:0xf
	v_max_u32_dpp v26, v26, v26 row_bcast:15 row_mask:0xa bank_mask:0xf
	v_max_u32_dpp v27, v27, v27 row_bcast:15 row_mask:0xa bank_mask:0xf
	v_max_u32_dpp v28, v28, v28 row_bcast:15 row_mask:0xa bank_mask:0xf
	v_max_u32_dpp v29, v29, v29 row_bcast:15 row_mask:0xa bank_mask:0xf
	v_max_u32_dpp v26, v26, v26 row_bcast:31 row_mask:0xc bank_mask:0xf
	v_max_u32_dpp v27, v27, v27 row_bcast:31 row_mask:0xc bank_mask:0xf
	v_max_u32_dpp v28, v28, v28 row_bcast:31 row_mask:0xc bank_mask:0xf
	v_max_u32_dpp v29, v29, v29 row_bcast:31 row_mask:0xc bank_mask:0xf
	v_readlane_b32 s14, v26, 63
	v_readlane_b32 s15, v27, 63
	v_readlane_b32 s34, v28, 63
	v_readlane_b32 s35, v29, 63
	v_writelane_b32 v82, s14, 1
	v_writelane_b32 v83, s15, 1
	v_writelane_b32 v84, s34, 1
	v_writelane_b32 v85, s35, 1
	v_cmp_ne_u32_e64 s[42:43], s14, v18
	v_cmp_ne_u32_e64 s[66:67], s14, v22
	v_cmp_ne_u32_e64 s[0:1], s15, v19
	v_cmp_ne_u32_e32 vcc, s15, v23
	v_cndmask_b32_e64 v18, 0, v18, s[42:43]
	v_cndmask_b32_e64 v22, 0, v22, s[66:67]
	v_cndmask_b32_e64 v19, 0, v19, s[0:1]
	v_cndmask_b32_e32 v23, 0, v23, vcc
	v_cmp_ne_u32_e64 s[42:43], s34, v20
	v_cmp_ne_u32_e64 s[66:67], s34, v24
	v_cmp_ne_u32_e64 s[0:1], s35, v21
	v_cmp_ne_u32_e32 vcc, s35, v25
	v_cndmask_b32_e64 v20, 0, v20, s[42:43]
	v_cndmask_b32_e64 v24, 0, v24, s[66:67]
	v_cndmask_b32_e64 v21, 0, v21, s[0:1]
	v_cndmask_b32_e32 v25, 0, v25, vcc
	v_max_u32_e32 v26, v18, v22
	v_max_u32_e32 v27, v19, v23
	v_max_u32_e32 v28, v20, v24
	v_max_u32_e32 v29, v21, v25
	v_max_u32_dpp v26, v26, v26 quad_perm:[1,0,3,2] row_mask:0xf bank_mask:0xf
	v_max_u32_dpp v27, v27, v27 quad_perm:[1,0,3,2] row_mask:0xf bank_mask:0xf
	v_max_u32_dpp v28, v28, v28 quad_perm:[1,0,3,2] row_mask:0xf bank_mask:0xf
	v_max_u32_dpp v29, v29, v29 quad_perm:[1,0,3,2] row_mask:0xf bank_mask:0xf
	v_max_u32_dpp v26, v26, v26 quad_perm:[2,3,0,1] row_mask:0xf bank_mask:0xf
	v_max_u32_dpp v27, v27, v27 quad_perm:[2,3,0,1] row_mask:0xf bank_mask:0xf
	v_max_u32_dpp v28, v28, v28 quad_perm:[2,3,0,1] row_mask:0xf bank_mask:0xf
	v_max_u32_dpp v29, v29, v29 quad_perm:[2,3,0,1] row_mask:0xf bank_mask:0xf
	v_max_u32_dpp v26, v26, v26 row_half_mirror row_mask:0xf bank_mask:0xf
	v_max_u32_dpp v27, v27, v27 row_half_mirror row_mask:0xf bank_mask:0xf
	v_max_u32_dpp v28, v28, v28 row_half_mirror row_mask:0xf bank_mask:0xf
	v_max_u32_dpp v29, v29, v29 row_half_mirror row_mask:0xf bank_mask:0xf
	v_max_u32_dpp v26, v26, v26 row_mirror row_mask:0xf bank_mask:0xf
	v_max_u32_dpp v27, v27, v27 row_mirror row_mask:0xf bank_mask:0xf
	v_max_u32_dpp v28, v28, v28 row_mirror row_mask:0xf bank_mask:0xf
	v_max_u32_dpp v29, v29, v29 row_mirror row_mask:0xf bank_mask:0xf
	v_max_u32_dpp v26, v26, v26 row_bcast:15 row_mask:0xa bank_mask:0xf
	v_max_u32_dpp v27, v27, v27 row_bcast:15 row_mask:0xa bank_mask:0xf
; __device__ __forceinline__ void nsa_quad_pre(int bg, int quad, const bf16_t* Q, const bf16_t* KV, const bf16_t* KCMP, const bf16_t* VCMPT, const float* GN, bf16_t* ONSA, ...
;     ...
;             for (int it = 0; it < 13; ++it) {
;                 unsigned m = k0 > k1 ? k0 : k1;
; #pragma unroll
;                 for (int off = 32; off >= 1; off >>= 1) { const unsigned o = (unsigned)__shfl_xor((int)m, off); m = o > m ? o : m; }
;                 if (k0 == m) k0 = 0u; if (k1 == m) k1 = 0u;
;                 if (lane == 0) selq[tt * 16 + it] = 127 - (int)(m & 127u);
	v_max_u32_dpp v28, v28, v28 row_bcast:15 row_mask:0xa bank_mask:0xf
	v_max_u32_dpp v29, v29, v29 row_bcast:15 row_mask:0xa bank_mask:0xf
	v_max_u32_dpp v26, v26, v26 row_bcast:31 row_mask:0xc bank_mask:0xf
	v_max_u32_dpp v27, v27, v27 row_bcast:31 row_mask:0xc bank_mask:0xf
	v_max_u32_dpp v28, v28, v28 row_bcast:31 row_mask:0xc bank_mask:0xf
	v_max_u32_dpp v29, v29, v29 row_bcast:31 row_mask:0xc bank_mask:0xf
	v_readlane_b32 s14, v26, 63
	v_readlane_b32 s15, v27, 63
	v_readlane_b32 s34, v28, 63
	v_readlane_b32 s35, v29, 63
	v_writelane_b32 v82, s14, 2
	v_writelane_b32 v83, s15, 2
	v_writelane_b32 v84, s34, 2
	v_writelane_b32 v85, s35, 2
	v_cmp_ne_u32_e64 s[42:43], s14, v18
	v_cmp_ne_u32_e64 s[66:67], s14, v22
	v_cmp_ne_u32_e64 s[0:1], s15, v19
	v_cmp_ne_u32_e32 vcc, s15, v23
	v_cndmask_b32_e64 v18, 0, v18, s[42:43]
	v_cndmask_b32_e64 v22, 0, v22, s[66:67]
	v_cndmask_b32_e64 v19, 0, v19, s[0:1]
	v_cndmask_b32_e32 v23, 0, v23, vcc
	v_cmp_ne_u32_e64 s[42:43], s34, v20
	v_cmp_ne_u32_e64 s[66:67], s34, v24
	v_cmp_ne_u32_e64 s[0:1], s35, v21
	v_cmp_ne_u32_e32 vcc, s35, v25
	v_cndmask_b32_e64 v20, 0, v20, s[42:43]
	v_cndmask_b32_e64 v24, 0, v24, s[66:67]
	v_cndmask_b32_e64 v21, 0, v21, s[0:1]
	v_cndmask_b32_e32 v25, 0, v25, vcc
	v_max_u32_e32 v26, v18, v22
	v_max_u32_e32 v27, v19, v23
	v_max_u32_e32 v28, v20, v24
	v_max_u32_e32 v29, v21, v25
	v_max_u32_dpp v26, v26, v26 quad_perm:[1,0,3,2] row_mask:0xf bank_mask:0xf
	v_max_u32_dpp v27, v27, v27 quad_perm:[1,0,3,2] row_mask:0xf bank_mask:0xf
	v_max_u32_dpp v28, v28, v28 quad_perm:[1,0,3,2] row_mask:0xf bank_mask:0xf
	v_max_u32_dpp v29, v29, v29 quad_perm:[1,0,3,2] row_mask:0xf bank_mask:0xf
	v_max_u32_dpp v26, v26, v26 quad_perm:[2,3,0,1] row_mask:0xf bank_mask:0xf
	v_max_u32_dpp v27, v27, v27 quad_perm:[2,3,0,1] row_mask:0xf bank_mask:0xf
	v_max_u32_dpp v28, v28, v28 quad_perm:[2,3,0,1] row_mask:0xf bank_mask:0xf
	v_max_u32_dpp v29, v29, v29 quad_perm:[2,3,0,1] row_mask:0xf bank_mask:0xf
	v_max_u32_dpp v26, v26, v26 row_half_mirror row_mask:0xf bank_mask:0xf
	v_max_u32_dpp v27, v27, v27 row_half_mirror row_mask:0xf bank_mask:0xf
	v_max_u32_dpp v28, v28, v28 row_half_mirror row_mask:0xf bank_mask:0xf
	v_max_u32_dpp v29, v29, v29 row_half_mirror row_mask:0xf bank_mask:0xf
	v_max_u32_dpp v26, v26, v26 row_mirror row_mask:0xf bank_mask:0xf
	v_max_u32_dpp v27, v27, v27 row_mirror row_mask:0xf bank_mask:0xf
	v_max_u32_dpp v28, v28, v28 row_mirror row_mask:0xf bank_mask:0xf
	v_max_u32_dpp v29, v29, v29 row_mirror row_mask:0xf bank_mask:0xf
	v_max_u32_dpp v26, v26, v26 row_bcast:15 row_mask:0xa bank_mask:0xf
	v_max_u32_dpp v27, v27, v27 row_bcast:15 row_mask:0xa bank_mask:0xf
	v_max_u32_dpp v28, v28, v28 row_bcast:15 row_mask:0xa bank_mask:0xf
	v_max_u32_dpp v29, v29, v29 row_bcast:15 row_mask:0xa bank_mask:0xf
	v_max_u32_dpp v26, v26, v26 row_bcast:31 row_mask:0xc bank_mask:0xf
	v_max_u32_dpp v27, v27, v27 row_bcast:31 row_mask:0xc bank_mask:0xf
	v_max_u32_dpp v28, v28, v28 row_bcast:31 row_mask:0xc bank_mask:0xf
	v_max_u32_dpp v29, v29, v29 row_bcast:31 row_mask:0xc bank_mask:0xf
	v_readlane_b32 s14, v26, 63
	v_readlane_b32 s15, v27, 63
	v_readlane_b32 s34, v28, 63
	v_readlane_b32 s35, v29, 63
	v_writelane_b32 v82, s14, 3
	v_writelane_b32 v83, s15, 3
	v_writelane_b32 v84, s34, 3
	v_writelane_b32 v85, s35, 3
	v_cmp_ne_u32_e64 s[42:43], s14, v18
	v_cmp_ne_u32_e64 s[66:67], s14, v22
	v_cmp_ne_u32_e64 s[0:1], s15, v19
	v_cmp_ne_u32_e32 vcc, s15, v23
	v_cndmask_b32_e64 v18, 0, v18, s[42:43]
	v_cndmask_b32_e64 v22, 0, v22, s[66:67]
	v_cndmask_b32_e64 v19, 0, v19, s[0:1]
	v_cndmask_b32_e32 v23, 0, v23, vcc
	v_cmp_ne_u32_e64 s[42:43], s34, v20
	v_cmp_ne_u32_e64 s[66:67], s34, v24
	v_cmp_ne_u32_e64 s[0:1], s35, v21
	v_cmp_ne_u32_e32 vcc, s35, v25
	v_cndmask_b32_e64 v20, 0, v20, s[42:43]
	v_cndmask_b32_e64 v24, 0, v24, s[66:67]
	v_cndmask_b32_e64 v21, 0, v21, s[0:1]
	v_cndmask_b32_e32 v25, 0, v25, vcc
	v_max_u32_e32 v26, v18, v22
	v_max_u32_e32 v27, v19, v23
	v_max_u32_e32 v28, v20, v24
	v_max_u32_e32 v29, v21, v25
	v_max_u32_dpp v26, v26, v26 quad_perm:[1,0,3,2] row_mask:0xf bank_mask:0xf
	v_max_u32_dpp v27, v27, v27 quad_perm:[1,0,3,2] row_mask:0xf bank_mask:0xf
	v_max_u32_dpp v28, v28, v28 quad_perm:[1,0,3,2] row_mask:0xf bank_mask:0xf
	v_max_u32_dpp v29, v29, v29 quad_perm:[1,0,3,2] row_mask:0xf bank_mask:0xf
	v_max_u32_dpp v26, v26, v26 quad_perm:[2,3,0,1] row_mask:0xf bank_mask:0xf
	v_max_u32_dpp v27, v27, v27 quad_perm:[2,3,0,1] row_mask:0xf bank_mask:0xf
	v_max_u32_dpp v28, v28, v28 quad_perm:[2,3,0,1] row_mask:0xf bank_mask:0xf
	v_max_u32_dpp v29, v29, v29 quad_perm:[2,3,0,1] row_mask:0xf bank_mask:0xf
	v_max_u32_dpp v26, v26, v26 row_half_mirror row_mask:0xf bank_mask:0xf
	v_max_u32_dpp v27, v27, v27 row_half_mirror row_mask:0xf bank_mask:0xf
	v_max_u32_dpp v28, v28, v28 row_half_mirror row_mask:0xf bank_mask:0xf
	v_max_u32_dpp v29, v29, v29 row_half_mirror row_mask:0xf bank_mask:0xf
	v_max_u32_dpp v26, v26, v26 row_mirror row_mask:0xf bank_mask:0xf
	v_max_u32_dpp v27, v27, v27 row_mirror row_mask:0xf bank_mask:0xf
	v_max_u32_dpp v28, v28, v28 row_mirror row_mask:0xf bank_mask:0xf
	v_max_u32_dpp v29, v29, v29 row_mirror row_mask:0xf bank_mask:0xf
	v_max_u32_dpp v26, v26, v26 row_bcast:15 row_mask:0xa bank_mask:0xf
	v_max_u32_dpp v27, v27, v27 row_bcast:15 row_mask:0xa bank_mask:0xf
	v_max_u32_dpp v28, v28, v28 row_bcast:15 row_mask:0xa bank_mask:0xf
	v_max_u32_dpp v29, v29, v29 row_bcast:15 row_mask:0xa bank_mask:0xf
	v_max_u32_dpp v26, v26, v26 row_bcast:31 row_mask:0xc bank_mask:0xf
	v_max_u32_dpp v27, v27, v27 row_bcast:31 row_mask:0xc bank_mask:0xf
	v_max_u32_dpp v28, v28, v28 row_bcast:31 row_mask:0xc bank_mask:0xf
; __device__ __forceinline__ void nsa_quad_pre(int bg, int quad, const bf16_t* Q, const bf16_t* KV, const bf16_t* KCMP, const bf16_t* VCMPT, const float* GN, bf16_t* ONSA, ...
;     ...
;             for (int it = 0; it < 13; ++it) {
;                 unsigned m = k0 > k1 ? k0 : k1;
; #pragma unroll
;                 for (int off = 32; off >= 1; off >>= 1) { const unsigned o = (unsigned)__shfl_xor((int)m, off); m = o > m ? o : m; }
;                 if (k0 == m) k0 = 0u; if (k1 == m) k1 = 0u;
;                 if (lane == 0) selq[tt * 16 + it] = 127 - (int)(m & 127u);
	v_max_u32_dpp v29, v29, v29 row_bcast:31 row_mask:0xc bank_mask:0xf
	v_readlane_b32 s14, v26, 63
	v_readlane_b32 s15, v27, 63
	v_readlane_b32 s34, v28, 63
	v_readlane_b32 s35, v29, 63
	v_writelane_b32 v82, s14, 4
	v_writelane_b32 v83, s15, 4
	v_writelane_b32 v84, s34, 4
	v_writelane_b32 v85, s35, 4
	v_cmp_ne_u32_e64 s[42:43], s14, v18
	v_cmp_ne_u32_e64 s[66:67], s14, v22
	v_cmp_ne_u32_e64 s[0:1], s15, v19
	v_cmp_ne_u32_e32 vcc, s15, v23
	v_cndmask_b32_e64 v18, 0, v18, s[42:43]
	v_cndmask_b32_e64 v22, 0, v22, s[66:67]
	v_cndmask_b32_e64 v19, 0, v19, s[0:1]
	v_cndmask_b32_e32 v23, 0, v23, vcc
	v_cmp_ne_u32_e64 s[42:43], s34, v20
	v_cmp_ne_u32_e64 s[66:67], s34, v24
	v_cmp_ne_u32_e64 s[0:1], s35, v21
	v_cmp_ne_u32_e32 vcc, s35, v25
	v_cndmask_b32_e64 v20, 0, v20, s[42:43]
	v_cndmask_b32_e64 v24, 0, v24, s[66:67]
	v_cndmask_b32_e64 v21, 0, v21, s[0:1]
	v_cndmask_b32_e32 v25, 0, v25, vcc
	v_max_u32_e32 v26, v18, v22
	v_max_u32_e32 v27, v19, v23
	v_max_u32_e32 v28, v20, v24
	v_max_u32_e32 v29, v21, v25
	v_max_u32_dpp v26, v26, v26 quad_perm:[1,0,3,2] row_mask:0xf bank_mask:0xf
	v_max_u32_dpp v27, v27, v27 quad_perm:[1,0,3,2] row_mask:0xf bank_mask:0xf
	v_max_u32_dpp v28, v28, v28 quad_perm:[1,0,3,2] row_mask:0xf bank_mask:0xf
	v_max_u32_dpp v29, v29, v29 quad_perm:[1,0,3,2] row_mask:0xf bank_mask:0xf
	v_max_u32_dpp v26, v26, v26 quad_perm:[2,3,0,1] row_mask:0xf bank_mask:0xf
	v_max_u32_dpp v27, v27, v27 quad_perm:[2,3,0,1] row_mask:0xf bank_mask:0xf
	v_max_u32_dpp v28, v28, v28 quad_perm:[2,3,0,1] row_mask:0xf bank_mask:0xf
	v_max_u32_dpp v29, v29, v29 quad_perm:[2,3,0,1] row_mask:0xf bank_mask:0xf
	v_max_u32_dpp v26, v26, v26 row_half_mirror row_mask:0xf bank_mask:0xf
	v_max_u32_dpp v27, v27, v27 row_half_mirror row_mask:0xf bank_mask:0xf
	v_max_u32_dpp v28, v28, v28 row_half_mirror row_mask:0xf bank_mask:0xf
	v_max_u32_dpp v29, v29, v29 row_half_mirror row_mask:0xf bank_mask:0xf
	v_max_u32_dpp v26, v26, v26 row_mirror row_mask:0xf bank_mask:0xf
	v_max_u32_dpp v27, v27, v27 row_mirror row_mask:0xf bank_mask:0xf
	v_max_u32_dpp v28, v28, v28 row_mirror row_mask:0xf bank_mask:0xf
	v_max_u32_dpp v29, v29, v29 row_mirror row_mask:0xf bank_mask:0xf
	v_max_u32_dpp v26, v26, v26 row_bcast:15 row_mask:0xa bank_mask:0xf
	v_max_u32_dpp v27, v27, v27 row_bcast:15 row_mask:0xa bank_mask:0xf
	v_max_u32_dpp v28, v28, v28 row_bcast:15 row_mask:0xa bank_mask:0xf
	v_max_u32_dpp v29, v29, v29 row_bcast:15 row_mask:0xa bank_mask:0xf
	v_max_u32_dpp v26, v26, v26 row_bcast:31 row_mask:0xc bank_mask:0xf
	v_max_u32_dpp v27, v27, v27 row_bcast:31 row_mask:0xc bank_mask:0xf
	v_max_u32_dpp v28, v28, v28 row_bcast:31 row_mask:0xc bank_mask:0xf
	v_max_u32_dpp v29, v29, v29 row_bcast:31 row_mask:0xc bank_mask:0xf
	v_readlane_b32 s14, v26, 63
	v_readlane_b32 s15, v27, 63
	v_readlane_b32 s34, v28, 63
	v_readlane_b32 s35, v29, 63
	v_writelane_b32 v82, s14, 5
	v_writelane_b32 v83, s15, 5
	v_writelane_b32 v84, s34, 5
	v_writelane_b32 v85, s35, 5
	v_cmp_ne_u32_e64 s[42:43], s14, v18
	v_cmp_ne_u32_e64 s[66:67], s14, v22
	v_cmp_ne_u32_e64 s[0:1], s15, v19
	v_cmp_ne_u32_e32 vcc, s15, v23
	v_cndmask_b32_e64 v18, 0, v18, s[42:43]
	v_cndmask_b32_e64 v22, 0, v22, s[66:67]
	v_cndmask_b32_e64 v19, 0, v19, s[0:1]
	v_cndmask_b32_e32 v23, 0, v23, vcc
	v_cmp_ne_u32_e64 s[42:43], s34, v20
	v_cmp_ne_u32_e64 s[66:67], s34, v24
	v_cmp_ne_u32_e64 s[0:1], s35, v21
	v_cmp_ne_u32_e32 vcc, s35, v25
	v_cndmask_b32_e64 v20, 0, v20, s[42:43]
	v_cndmask_b32_e64 v24, 0, v24, s[66:67]
	v_cndmask_b32_e64 v21, 0, v21, s[0:1]
	v_cndmask_b32_e32 v25, 0, v25, vcc
	v_max_u32_e32 v26, v18, v22
	v_max_u32_e32 v27, v19, v23
	v_max_u32_e32 v28, v20, v24
	v_max_u32_e32 v29, v21, v25
	v_max_u32_dpp v26, v26, v26 quad_perm:[1,0,3,2] row_mask:0xf bank_mask:0xf
	v_max_u32_dpp v27, v27, v27 quad_perm:[1,0,3,2] row_mask:0xf bank_mask:0xf
	v_max_u32_dpp v28, v28, v28 quad_perm:[1,0,3,2] row_mask:0xf bank_mask:0xf
	v_max_u32_dpp v29, v29, v29 quad_perm:[1,0,3,2] row_mask:0xf bank_mask:0xf
	v_max_u32_dpp v26, v26, v26 quad_perm:[2,3,0,1] row_mask:0xf bank_mask:0xf
	v_max_u32_dpp v27, v27, v27 quad_perm:[2,3,0,1] row_mask:0xf bank_mask:0xf
	v_max_u32_dpp v28, v28, v28 quad_perm:[2,3,0,1] row_mask:0xf bank_mask:0xf
	v_max_u32_dpp v29, v29, v29 quad_perm:[2,3,0,1] row_mask:0xf bank_mask:0xf
	v_max_u32_dpp v26, v26, v26 row_half_mirror row_mask:0xf bank_mask:0xf
	v_max_u32_dpp v27, v27, v27 row_half_mirror row_mask:0xf bank_mask:0xf
	v_max_u32_dpp v28, v28, v28 row_half_mirror row_mask:0xf bank_mask:0xf
	v_max_u32_dpp v29, v29, v29 row_half_mirror row_mask:0xf bank_mask:0xf
	v_max_u32_dpp v26, v26, v26 row_mirror row_mask:0xf bank_mask:0xf
	v_max_u32_dpp v27, v27, v27 row_mirror row_mask:0xf bank_mask:0xf
	v_max_u32_dpp v28, v28, v28 row_mirror row_mask:0xf bank_mask:0xf
	v_max_u32_dpp v29, v29, v29 row_mirror row_mask:0xf bank_mask:0xf
	v_max_u32_dpp v26, v26, v26 row_bcast:15 row_mask:0xa bank_mask:0xf
	v_max_u32_dpp v27, v27, v27 row_bcast:15 row_mask:0xa bank_mask:0xf
	v_max_u32_dpp v28, v28, v28 row_bcast:15 row_mask:0xa bank_mask:0xf
	v_max_u32_dpp v29, v29, v29 row_bcast:15 row_mask:0xa bank_mask:0xf
	v_max_u32_dpp v26, v26, v26 row_bcast:31 row_mask:0xc bank_mask:0xf
	v_max_u32_dpp v27, v27, v27 row_bcast:31 row_mask:0xc bank_mask:0xf
	v_max_u32_dpp v28, v28, v28 row_bcast:31 row_mask:0xc bank_mask:0xf
	v_max_u32_dpp v29, v29, v29 row_bcast:31 row_mask:0xc bank_mask:0xf
	v_readlane_b32 s14, v26, 63
	v_readlane_b32 s15, v27, 63
	v_readlane_b32 s34, v28, 63
	v_readlane_b32 s35, v29, 63
	v_writelane_b32 v82, s14, 6
	v_writelane_b32 v83, s15, 6
	v_writelane_b32 v84, s34, 6
	v_writelane_b32 v85, s35, 6
	v_cmp_ne_u32_e64 s[42:43], s14, v18
; __device__ __forceinline__ void nsa_quad_pre(int bg, int quad, const bf16_t* Q, const bf16_t* KV, const bf16_t* KCMP, const bf16_t* VCMPT, const float* GN, bf16_t* ONSA, ...
;     ...
;             for (int it = 0; it < 13; ++it) {
;                 unsigned m = k0 > k1 ? k0 : k1;
; #pragma unroll
;                 for (int off = 32; off >= 1; off >>= 1) { const unsigned o = (unsigned)__shfl_xor((int)m, off); m = o > m ? o : m; }
;                 if (k0 == m) k0 = 0u; if (k1 == m) k1 = 0u;
;                 if (lane == 0) selq[tt * 16 + it] = 127 - (int)(m & 127u);
	v_cmp_ne_u32_e64 s[66:67], s14, v22
	v_cmp_ne_u32_e64 s[0:1], s15, v19
	v_cmp_ne_u32_e32 vcc, s15, v23
	v_cndmask_b32_e64 v18, 0, v18, s[42:43]
	v_cndmask_b32_e64 v22, 0, v22, s[66:67]
	v_cndmask_b32_e64 v19, 0, v19, s[0:1]
	v_cndmask_b32_e32 v23, 0, v23, vcc
	v_cmp_ne_u32_e64 s[42:43], s34, v20
	v_cmp_ne_u32_e64 s[66:67], s34, v24
	v_cmp_ne_u32_e64 s[0:1], s35, v21
	v_cmp_ne_u32_e32 vcc, s35, v25
	v_cndmask_b32_e64 v20, 0, v20, s[42:43]
	v_cndmask_b32_e64 v24, 0, v24, s[66:67]
	v_cndmask_b32_e64 v21, 0, v21, s[0:1]
	v_cndmask_b32_e32 v25, 0, v25, vcc
	v_max_u32_e32 v26, v18, v22
	v_max_u32_e32 v27, v19, v23
	v_max_u32_e32 v28, v20, v24
	v_max_u32_e32 v29, v21, v25
	v_max_u32_dpp v26, v26, v26 quad_perm:[1,0,3,2] row_mask:0xf bank_mask:0xf
	v_max_u32_dpp v27, v27, v27 quad_perm:[1,0,3,2] row_mask:0xf bank_mask:0xf
	v_max_u32_dpp v28, v28, v28 quad_perm:[1,0,3,2] row_mask:0xf bank_mask:0xf
	v_max_u32_dpp v29, v29, v29 quad_perm:[1,0,3,2] row_mask:0xf bank_mask:0xf
	v_max_u32_dpp v26, v26, v26 quad_perm:[2,3,0,1] row_mask:0xf bank_mask:0xf
	v_max_u32_dpp v27, v27, v27 quad_perm:[2,3,0,1] row_mask:0xf bank_mask:0xf
	v_max_u32_dpp v28, v28, v28 quad_perm:[2,3,0,1] row_mask:0xf bank_mask:0xf
	v_max_u32_dpp v29, v29, v29 quad_perm:[2,3,0,1] row_mask:0xf bank_mask:0xf
	v_max_u32_dpp v26, v26, v26 row_half_mirror row_mask:0xf bank_mask:0xf
	v_max_u32_dpp v27, v27, v27 row_half_mirror row_mask:0xf bank_mask:0xf
	v_max_u32_dpp v28, v28, v28 row_half_mirror row_mask:0xf bank_mask:0xf
	v_max_u32_dpp v29, v29, v29 row_half_mirror row_mask:0xf bank_mask:0xf
	v_max_u32_dpp v26, v26, v26 row_mirror row_mask:0xf bank_mask:0xf
	v_max_u32_dpp v27, v27, v27 row_mirror row_mask:0xf bank_mask:0xf
	v_max_u32_dpp v28, v28, v28 row_mirror row_mask:0xf bank_mask:0xf
	v_max_u32_dpp v29, v29, v29 row_mirror row_mask:0xf bank_mask:0xf
	v_max_u32_dpp v26, v26, v26 row_bcast:15 row_mask:0xa bank_mask:0xf
	v_max_u32_dpp v27, v27, v27 row_bcast:15 row_mask:0xa bank_mask:0xf
	v_max_u32_dpp v28, v28, v28 row_bcast:15 row_mask:0xa bank_mask:0xf
	v_max_u32_dpp v29, v29, v29 row_bcast:15 row_mask:0xa bank_mask:0xf
	v_max_u32_dpp v26, v26, v26 row_bcast:31 row_mask:0xc bank_mask:0xf
	v_max_u32_dpp v27, v27, v27 row_bcast:31 row_mask:0xc bank_mask:0xf
	v_max_u32_dpp v28, v28, v28 row_bcast:31 row_mask:0xc bank_mask:0xf
	v_max_u32_dpp v29, v29, v29 row_bcast:31 row_mask:0xc bank_mask:0xf
	v_readlane_b32 s14, v26, 63
	v_readlane_b32 s15, v27, 63
	v_readlane_b32 s34, v28, 63
	v_readlane_b32 s35, v29, 63
	v_writelane_b32 v82, s14, 7
	v_writelane_b32 v83, s15, 7
	v_writelane_b32 v84, s34, 7
	v_writelane_b32 v85, s35, 7
	v_cmp_ne_u32_e64 s[42:43], s14, v18
	v_cmp_ne_u32_e64 s[66:67], s14, v22
	v_cmp_ne_u32_e64 s[0:1], s15, v19
	v_cmp_ne_u32_e32 vcc, s15, v23
	v_cndmask_b32_e64 v18, 0, v18, s[42:43]
	v_cndmask_b32_e64 v22, 0, v22, s[66:67]
	v_cndmask_b32_e64 v19, 0, v19, s[0:1]
	v_cndmask_b32_e32 v23, 0, v23, vcc
	v_cmp_ne_u32_e64 s[42:43], s34, v20
	v_cmp_ne_u32_e64 s[66:67], s34, v24
	v_cmp_ne_u32_e64 s[0:1], s35, v21
	v_cmp_ne_u32_e32 vcc, s35, v25
	v_cndmask_b32_e64 v20, 0, v20, s[42:43]
	v_cndmask_b32_e64 v24, 0, v24, s[66:67]
	v_cndmask_b32_e64 v21, 0, v21, s[0:1]
	v_cndmask_b32_e32 v25, 0, v25, vcc
	v_max_u32_e32 v26, v18, v22
	v_max_u32_e32 v27, v19, v23
	v_max_u32_e32 v28, v20, v24
	v_max_u32_e32 v29, v21, v25
	v_max_u32_dpp v26, v26, v26 quad_perm:[1,0,3,2] row_mask:0xf bank_mask:0xf
	v_max_u32_dpp v27, v27, v27 quad_perm:[1,0,3,2] row_mask:0xf bank_mask:0xf
	v_max_u32_dpp v28, v28, v28 quad_perm:[1,0,3,2] row_mask:0xf bank_mask:0xf
	v_max_u32_dpp v29, v29, v29 quad_perm:[1,0,3,2] row_mask:0xf bank_mask:0xf
	v_max_u32_dpp v26, v26, v26 quad_perm:[2,3,0,1] row_mask:0xf bank_mask:0xf
	v_max_u32_dpp v27, v27, v27 quad_perm:[2,3,0,1] row_mask:0xf bank_mask:0xf
	v_max_u32_dpp v28, v28, v28 quad_perm:[2,3,0,1] row_mask:0xf bank_mask:0xf
	v_max_u32_dpp v29, v29, v29 quad_perm:[2,3,0,1] row_mask:0xf bank_mask:0xf
	v_max_u32_dpp v26, v26, v26 row_half_mirror row_mask:0xf bank_mask:0xf
	v_max_u32_dpp v27, v27, v27 row_half_mirror row_mask:0xf bank_mask:0xf
	v_max_u32_dpp v28, v28, v28 row_half_mirror row_mask:0xf bank_mask:0xf
	v_max_u32_dpp v29, v29, v29 row_half_mirror row_mask:0xf bank_mask:0xf
	v_max_u32_dpp v26, v26, v26 row_mirror row_mask:0xf bank_mask:0xf
	v_max_u32_dpp v27, v27, v27 row_mirror row_mask:0xf bank_mask:0xf
	v_max_u32_dpp v28, v28, v28 row_mirror row_mask:0xf bank_mask:0xf
	v_max_u32_dpp v29, v29, v29 row_mirror row_mask:0xf bank_mask:0xf
	v_max_u32_dpp v26, v26, v26 row_bcast:15 row_mask:0xa bank_mask:0xf
	v_max_u32_dpp v27, v27, v27 row_bcast:15 row_mask:0xa bank_mask:0xf
	v_max_u32_dpp v28, v28, v28 row_bcast:15 row_mask:0xa bank_mask:0xf
	v_max_u32_dpp v29, v29, v29 row_bcast:15 row_mask:0xa bank_mask:0xf
	v_max_u32_dpp v26, v26, v26 row_bcast:31 row_mask:0xc bank_mask:0xf
	v_max_u32_dpp v27, v27, v27 row_bcast:31 row_mask:0xc bank_mask:0xf
	v_max_u32_dpp v28, v28, v28 row_bcast:31 row_mask:0xc bank_mask:0xf
	v_max_u32_dpp v29, v29, v29 row_bcast:31 row_mask:0xc bank_mask:0xf
	v_readlane_b32 s14, v26, 63
	v_readlane_b32 s15, v27, 63
	v_readlane_b32 s34, v28, 63
	v_readlane_b32 s35, v29, 63
	v_writelane_b32 v82, s14, 8
	v_writelane_b32 v83, s15, 8
	v_writelane_b32 v84, s34, 8
	v_writelane_b32 v85, s35, 8
	v_cmp_ne_u32_e64 s[42:43], s14, v18
	v_cmp_ne_u32_e64 s[66:67], s14, v22
	v_cmp_ne_u32_e64 s[0:1], s15, v19
	v_cmp_ne_u32_e32 vcc, s15, v23
	v_cndmask_b32_e64 v18, 0, v18, s[42:43]
	v_cndmask_b32_e64 v22, 0, v22, s[66:67]
	v_cndmask_b32_e64 v19, 0, v19, s[0:1]
	v_cndmask_b32_e32 v23, 0, v23, vcc
	v_cmp_ne_u32_e64 s[42:43], s34, v20
	v_cmp_ne_u32_e64 s[66:67], s34, v24
; __device__ __forceinline__ void nsa_quad_pre(int bg, int quad, const bf16_t* Q, const bf16_t* KV, const bf16_t* KCMP, const bf16_t* VCMPT, const float* GN, bf16_t* ONSA, ...
;     ...
;             for (int it = 0; it < 13; ++it) {
;                 unsigned m = k0 > k1 ? k0 : k1;
; #pragma unroll
;                 for (int off = 32; off >= 1; off >>= 1) { const unsigned o = (unsigned)__shfl_xor((int)m, off); m = o > m ? o : m; }
;                 if (k0 == m) k0 = 0u; if (k1 == m) k1 = 0u;
;                 if (lane == 0) selq[tt * 16 + it] = 127 - (int)(m & 127u);
	v_cmp_ne_u32_e64 s[0:1], s35, v21
	v_cmp_ne_u32_e32 vcc, s35, v25
	v_cndmask_b32_e64 v20, 0, v20, s[42:43]
	v_cndmask_b32_e64 v24, 0, v24, s[66:67]
	v_cndmask_b32_e64 v21, 0, v21, s[0:1]
	v_cndmask_b32_e32 v25, 0, v25, vcc
	v_max_u32_e32 v26, v18, v22
	v_max_u32_e32 v27, v19, v23
	v_max_u32_e32 v28, v20, v24
	v_max_u32_e32 v29, v21, v25
	v_max_u32_dpp v26, v26, v26 quad_perm:[1,0,3,2] row_mask:0xf bank_mask:0xf
	v_max_u32_dpp v27, v27, v27 quad_perm:[1,0,3,2] row_mask:0xf bank_mask:0xf
	v_max_u32_dpp v28, v28, v28 quad_perm:[1,0,3,2] row_mask:0xf bank_mask:0xf
	v_max_u32_dpp v29, v29, v29 quad_perm:[1,0,3,2] row_mask:0xf bank_mask:0xf
	v_max_u32_dpp v26, v26, v26 quad_perm:[2,3,0,1] row_mask:0xf bank_mask:0xf
	v_max_u32_dpp v27, v27, v27 quad_perm:[2,3,0,1] row_mask:0xf bank_mask:0xf
	v_max_u32_dpp v28, v28, v28 quad_perm:[2,3,0,1] row_mask:0xf bank_mask:0xf
	v_max_u32_dpp v29, v29, v29 quad_perm:[2,3,0,1] row_mask:0xf bank_mask:0xf
	v_max_u32_dpp v26, v26, v26 row_half_mirror row_mask:0xf bank_mask:0xf
	v_max_u32_dpp v27, v27, v27 row_half_mirror row_mask:0xf bank_mask:0xf
	v_max_u32_dpp v28, v28, v28 row_half_mirror row_mask:0xf bank_mask:0xf
	v_max_u32_dpp v29, v29, v29 row_half_mirror row_mask:0xf bank_mask:0xf
	v_max_u32_dpp v26, v26, v26 row_mirror row_mask:0xf bank_mask:0xf
	v_max_u32_dpp v27, v27, v27 row_mirror row_mask:0xf bank_mask:0xf
	v_max_u32_dpp v28, v28, v28 row_mirror row_mask:0xf bank_mask:0xf
	v_max_u32_dpp v29, v29, v29 row_mirror row_mask:0xf bank_mask:0xf
	v_max_u32_dpp v26, v26, v26 row_bcast:15 row_mask:0xa bank_mask:0xf
	v_max_u32_dpp v27, v27, v27 row_bcast:15 row_mask:0xa bank_mask:0xf
	v_max_u32_dpp v28, v28, v28 row_bcast:15 row_mask:0xa bank_mask:0xf
	v_max_u32_dpp v29, v29, v29 row_bcast:15 row_mask:0xa bank_mask:0xf
	v_max_u32_dpp v26, v26, v26 row_bcast:31 row_mask:0xc bank_mask:0xf
	v_max_u32_dpp v27, v27, v27 row_bcast:31 row_mask:0xc bank_mask:0xf
	v_max_u32_dpp v28, v28, v28 row_bcast:31 row_mask:0xc bank_mask:0xf
	v_max_u32_dpp v29, v29, v29 row_bcast:31 row_mask:0xc bank_mask:0xf
	v_readlane_b32 s14, v26, 63
	v_readlane_b32 s15, v27, 63
	v_readlane_b32 s34, v28, 63
	v_readlane_b32 s35, v29, 63
	v_writelane_b32 v82, s14, 9
	v_writelane_b32 v83, s15, 9
	v_writelane_b32 v84, s34, 9
	v_writelane_b32 v85, s35, 9
	v_cmp_ne_u32_e64 s[42:43], s14, v18
	v_cmp_ne_u32_e64 s[66:67], s14, v22
	v_cmp_ne_u32_e64 s[0:1], s15, v19
	v_cmp_ne_u32_e32 vcc, s15, v23
	v_cndmask_b32_e64 v18, 0, v18, s[42:43]
	v_cndmask_b32_e64 v22, 0, v22, s[66:67]
	v_cndmask_b32_e64 v19, 0, v19, s[0:1]
	v_cndmask_b32_e32 v23, 0, v23, vcc
	v_cmp_ne_u32_e64 s[42:43], s34, v20
	v_cmp_ne_u32_e64 s[66:67], s34, v24
	v_cmp_ne_u32_e64 s[0:1], s35, v21
	v_cmp_ne_u32_e32 vcc, s35, v25
	v_cndmask_b32_e64 v20, 0, v20, s[42:43]
	v_cndmask_b32_e64 v24, 0, v24, s[66:67]
	v_cndmask_b32_e64 v21, 0, v21, s[0:1]
	v_cndmask_b32_e32 v25, 0, v25, vcc
	v_max_u32_e32 v26, v18, v22
	v_max_u32_e32 v27, v19, v23
	v_max_u32_e32 v28, v20, v24
	v_max_u32_e32 v29, v21, v25
	v_max_u32_dpp v26, v26, v26 quad_perm:[1,0,3,2] row_mask:0xf bank_mask:0xf
	v_max_u32_dpp v27, v27, v27 quad_perm:[1,0,3,2] row_mask:0xf bank_mask:0xf
	v_max_u32_dpp v28, v28, v28 quad_perm:[1,0,3,2] row_mask:0xf bank_mask:0xf
	v_max_u32_dpp v29, v29, v29 quad_perm:[1,0,3,2] row_mask:0xf bank_mask:0xf
	v_max_u32_dpp v26, v26, v26 quad_perm:[2,3,0,1] row_mask:0xf bank_mask:0xf
	v_max_u32_dpp v27, v27, v27 quad_perm:[2,3,0,1] row_mask:0xf bank_mask:0xf
	v_max_u32_dpp v28, v28, v28 quad_perm:[2,3,0,1] row_mask:0xf bank_mask:0xf
	v_max_u32_dpp v29, v29, v29 quad_perm:[2,3,0,1] row_mask:0xf bank_mask:0xf
	v_max_u32_dpp v26, v26, v26 row_half_mirror row_mask:0xf bank_mask:0xf
	v_max_u32_dpp v27, v27, v27 row_half_mirror row_mask:0xf bank_mask:0xf
	v_max_u32_dpp v28, v28, v28 row_half_mirror row_mask:0xf bank_mask:0xf
	v_max_u32_dpp v29, v29, v29 row_half_mirror row_mask:0xf bank_mask:0xf
	v_max_u32_dpp v26, v26, v26 row_mirror row_mask:0xf bank_mask:0xf
	v_max_u32_dpp v27, v27, v27 row_mirror row_mask:0xf bank_mask:0xf
	v_max_u32_dpp v28, v28, v28 row_mirror row_mask:0xf bank_mask:0xf
	v_max_u32_dpp v29, v29, v29 row_mirror row_mask:0xf bank_mask:0xf
	v_max_u32_dpp v26, v26, v26 row_bcast:15 row_mask:0xa bank_mask:0xf
	v_max_u32_dpp v27, v27, v27 row_bcast:15 row_mask:0xa bank_mask:0xf
	v_max_u32_dpp v28, v28, v28 row_bcast:15 row_mask:0xa bank_mask:0xf
	v_max_u32_dpp v29, v29, v29 row_bcast:15 row_mask:0xa bank_mask:0xf
	v_max_u32_dpp v26, v26, v26 row_bcast:31 row_mask:0xc bank_mask:0xf
	v_max_u32_dpp v27, v27, v27 row_bcast:31 row_mask:0xc bank_mask:0xf
	v_max_u32_dpp v28, v28, v28 row_bcast:31 row_mask:0xc bank_mask:0xf
	v_max_u32_dpp v29, v29, v29 row_bcast:31 row_mask:0xc bank_mask:0xf
	v_readlane_b32 s14, v26, 63
	v_readlane_b32 s15, v27, 63
	v_readlane_b32 s34, v28, 63
	v_readlane_b32 s35, v29, 63
	v_writelane_b32 v82, s14, 10
	v_writelane_b32 v83, s15, 10
	v_writelane_b32 v84, s34, 10
	v_writelane_b32 v85, s35, 10
	v_cmp_ne_u32_e64 s[42:43], s14, v18
	v_cmp_ne_u32_e64 s[66:67], s14, v22
	v_cmp_ne_u32_e64 s[0:1], s15, v19
	v_cmp_ne_u32_e32 vcc, s15, v23
	v_cndmask_b32_e64 v18, 0, v18, s[42:43]
	v_cndmask_b32_e64 v22, 0, v22, s[66:67]
	v_cndmask_b32_e64 v19, 0, v19, s[0:1]
	v_cndmask_b32_e32 v23, 0, v23, vcc
	v_cmp_ne_u32_e64 s[42:43], s34, v20
	v_cmp_ne_u32_e64 s[66:67], s34, v24
	v_cmp_ne_u32_e64 s[0:1], s35, v21
	v_cmp_ne_u32_e32 vcc, s35, v25
	v_cndmask_b32_e64 v20, 0, v20, s[42:43]
	v_cndmask_b32_e64 v24, 0, v24, s[66:67]
	v_cndmask_b32_e64 v21, 0, v21, s[0:1]
	v_cndmask_b32_e32 v25, 0, v25, vcc
	v_max_u32_e32 v26, v18, v22
	v_max_u32_e32 v27, v19, v23
	v_max_u32_e32 v28, v20, v24
; __device__ __forceinline__ void nsa_quad_pre(int bg, int quad, const bf16_t* Q, const bf16_t* KV, const bf16_t* KCMP, const bf16_t* VCMPT, const float* GN, bf16_t* ONSA, ...
;     ...
;             for (int it = 0; it < 13; ++it) {
;                 unsigned m = k0 > k1 ? k0 : k1;
; #pragma unroll
;                 for (int off = 32; off >= 1; off >>= 1) { const unsigned o = (unsigned)__shfl_xor((int)m, off); m = o > m ? o : m; }
;                 if (k0 == m) k0 = 0u; if (k1 == m) k1 = 0u;
;                 if (lane == 0) selq[tt * 16 + it] = 127 - (int)(m & 127u);
;             }
;             if (lane == 0) { selq[tt * 16 + 13] = 0; selq[tt * 16 + 14] = cur - 1; selq[tt * 16 + 15] = cur; }
	v_max_u32_e32 v29, v21, v25
	v_max_u32_dpp v26, v26, v26 quad_perm:[1,0,3,2] row_mask:0xf bank_mask:0xf
	v_max_u32_dpp v27, v27, v27 quad_perm:[1,0,3,2] row_mask:0xf bank_mask:0xf
	v_max_u32_dpp v28, v28, v28 quad_perm:[1,0,3,2] row_mask:0xf bank_mask:0xf
	v_max_u32_dpp v29, v29, v29 quad_perm:[1,0,3,2] row_mask:0xf bank_mask:0xf
	v_max_u32_dpp v26, v26, v26 quad_perm:[2,3,0,1] row_mask:0xf bank_mask:0xf
	v_max_u32_dpp v27, v27, v27 quad_perm:[2,3,0,1] row_mask:0xf bank_mask:0xf
	v_max_u32_dpp v28, v28, v28 quad_perm:[2,3,0,1] row_mask:0xf bank_mask:0xf
	v_max_u32_dpp v29, v29, v29 quad_perm:[2,3,0,1] row_mask:0xf bank_mask:0xf
	v_max_u32_dpp v26, v26, v26 row_half_mirror row_mask:0xf bank_mask:0xf
	v_max_u32_dpp v27, v27, v27 row_half_mirror row_mask:0xf bank_mask:0xf
	v_max_u32_dpp v28, v28, v28 row_half_mirror row_mask:0xf bank_mask:0xf
	v_max_u32_dpp v29, v29, v29 row_half_mirror row_mask:0xf bank_mask:0xf
	v_max_u32_dpp v26, v26, v26 row_mirror row_mask:0xf bank_mask:0xf
	v_max_u32_dpp v27, v27, v27 row_mirror row_mask:0xf bank_mask:0xf
	v_max_u32_dpp v28, v28, v28 row_mirror row_mask:0xf bank_mask:0xf
	v_max_u32_dpp v29, v29, v29 row_mirror row_mask:0xf bank_mask:0xf
	v_max_u32_dpp v26, v26, v26 row_bcast:15 row_mask:0xa bank_mask:0xf
	v_max_u32_dpp v27, v27, v27 row_bcast:15 row_mask:0xa bank_mask:0xf
	v_max_u32_dpp v28, v28, v28 row_bcast:15 row_mask:0xa bank_mask:0xf
	v_max_u32_dpp v29, v29, v29 row_bcast:15 row_mask:0xa bank_mask:0xf
	v_max_u32_dpp v26, v26, v26 row_bcast:31 row_mask:0xc bank_mask:0xf
	v_max_u32_dpp v27, v27, v27 row_bcast:31 row_mask:0xc bank_mask:0xf
	v_max_u32_dpp v28, v28, v28 row_bcast:31 row_mask:0xc bank_mask:0xf
	v_max_u32_dpp v29, v29, v29 row_bcast:31 row_mask:0xc bank_mask:0xf
	v_readlane_b32 s14, v26, 63
	v_readlane_b32 s15, v27, 63
	v_readlane_b32 s34, v28, 63
	v_readlane_b32 s35, v29, 63
	v_writelane_b32 v82, s14, 11
	v_writelane_b32 v83, s15, 11
	v_writelane_b32 v84, s34, 11
	v_writelane_b32 v85, s35, 11
	v_cmp_ne_u32_e64 s[42:43], s14, v18
	v_cmp_ne_u32_e64 s[66:67], s14, v22
	v_cmp_ne_u32_e64 s[0:1], s15, v19
	v_cmp_ne_u32_e32 vcc, s15, v23
	v_cndmask_b32_e64 v18, 0, v18, s[42:43]
	v_cndmask_b32_e64 v22, 0, v22, s[66:67]
	v_cndmask_b32_e64 v19, 0, v19, s[0:1]
	v_cndmask_b32_e32 v23, 0, v23, vcc
	v_cmp_ne_u32_e64 s[42:43], s34, v20
	v_cmp_ne_u32_e64 s[66:67], s34, v24
	v_cmp_ne_u32_e64 s[0:1], s35, v21
	v_cmp_ne_u32_e32 vcc, s35, v25
	v_cndmask_b32_e64 v20, 0, v20, s[42:43]
	v_cndmask_b32_e64 v24, 0, v24, s[66:67]
	v_cndmask_b32_e64 v21, 0, v21, s[0:1]
	v_cndmask_b32_e32 v25, 0, v25, vcc
	v_max_u32_e32 v26, v18, v22
	v_max_u32_e32 v27, v19, v23
	v_max_u32_e32 v28, v20, v24
	v_max_u32_e32 v29, v21, v25
	v_max_u32_dpp v26, v26, v26 quad_perm:[1,0,3,2] row_mask:0xf bank_mask:0xf
	v_max_u32_dpp v27, v27, v27 quad_perm:[1,0,3,2] row_mask:0xf bank_mask:0xf
	v_max_u32_dpp v28, v28, v28 quad_perm:[1,0,3,2] row_mask:0xf bank_mask:0xf
	v_max_u32_dpp v29, v29, v29 quad_perm:[1,0,3,2] row_mask:0xf bank_mask:0xf
	v_max_u32_dpp v26, v26, v26 quad_perm:[2,3,0,1] row_mask:0xf bank_mask:0xf
	v_max_u32_dpp v27, v27, v27 quad_perm:[2,3,0,1] row_mask:0xf bank_mask:0xf
	v_max_u32_dpp v28, v28, v28 quad_perm:[2,3,0,1] row_mask:0xf bank_mask:0xf
	v_max_u32_dpp v29, v29, v29 quad_perm:[2,3,0,1] row_mask:0xf bank_mask:0xf
	v_max_u32_dpp v26, v26, v26 row_half_mirror row_mask:0xf bank_mask:0xf
	v_max_u32_dpp v27, v27, v27 row_half_mirror row_mask:0xf bank_mask:0xf
	v_max_u32_dpp v28, v28, v28 row_half_mirror row_mask:0xf bank_mask:0xf
	v_max_u32_dpp v29, v29, v29 row_half_mirror row_mask:0xf bank_mask:0xf
	v_max_u32_dpp v26, v26, v26 row_mirror row_mask:0xf bank_mask:0xf
	v_max_u32_dpp v27, v27, v27 row_mirror row_mask:0xf bank_mask:0xf
	v_max_u32_dpp v28, v28, v28 row_mirror row_mask:0xf bank_mask:0xf
	v_max_u32_dpp v29, v29, v29 row_mirror row_mask:0xf bank_mask:0xf
	v_max_u32_dpp v26, v26, v26 row_bcast:15 row_mask:0xa bank_mask:0xf
	v_max_u32_dpp v27, v27, v27 row_bcast:15 row_mask:0xa bank_mask:0xf
	v_max_u32_dpp v28, v28, v28 row_bcast:15 row_mask:0xa bank_mask:0xf
	v_max_u32_dpp v29, v29, v29 row_bcast:15 row_mask:0xa bank_mask:0xf
	v_max_u32_dpp v26, v26, v26 row_bcast:31 row_mask:0xc bank_mask:0xf
	v_max_u32_dpp v27, v27, v27 row_bcast:31 row_mask:0xc bank_mask:0xf
	v_max_u32_dpp v28, v28, v28 row_bcast:31 row_mask:0xc bank_mask:0xf
	v_max_u32_dpp v29, v29, v29 row_bcast:31 row_mask:0xc bank_mask:0xf
	v_readlane_b32 s14, v26, 63
	v_readlane_b32 s15, v27, 63
	v_readlane_b32 s34, v28, 63
	v_readlane_b32 s35, v29, 63
	v_writelane_b32 v82, s14, 12
	v_writelane_b32 v83, s15, 12
	v_writelane_b32 v84, s34, 12
	v_writelane_b32 v85, s35, 12
	v_and_b32_e32 v82, 127, v82
	v_sub_u32_e32 v82, 127, v82
	v_and_b32_e32 v83, 127, v83
	v_sub_u32_e32 v83, 127, v83
	v_and_b32_e32 v84, 127, v84
	v_sub_u32_e32 v84, 127, v84
	v_and_b32_e32 v85, 127, v85
	v_sub_u32_e32 v85, 127, v85
	s_add_i32 s19, s18, -1
	v_mov_b32_e32 v236, s19
	v_mov_b32_e32 v237, s18
	v_cmp_eq_u32_e64 s[14:15], 14, v184
	v_cmp_eq_u32_e64 s[34:35], 15, v184
	s_nop 0
	v_cndmask_b32_e64 v82, v82, v236, s[14:15]
	v_cndmask_b32_e64 v82, v82, v237, s[34:35]
	v_cndmask_b32_e64 v83, v83, v236, s[14:15]
	v_cndmask_b32_e64 v83, v83, v237, s[34:35]
	v_cndmask_b32_e64 v84, v84, v236, s[14:15]
	v_cndmask_b32_e64 v84, v84, v237, s[34:35]
	v_cndmask_b32_e64 v85, v85, v236, s[14:15]
	v_cndmask_b32_e64 v85, v85, v237, s[34:35]
	s_and_saveexec_b64 s[42:43], s[6:7]
	ds_write_b32 v196, v82 offset:51264
	ds_write_b32 v196, v83 offset:51328
	ds_write_b32 v196, v84 offset:51392
	ds_write_b32 v196, v85 offset:51456
	s_or_b64 exec, exec, s[42:43]
	s_branch .Ltopk_done_q0

; __device__ __forceinline__ void nsa_quad_pre(int bg, int quad, const bf16_t* Q, const bf16_t* KV, const bf16_t* KCMP, const bf16_t* VCMPT, const float* GN, bf16_t* ONSA, ...
;     ...
;     const int w_lo = (t0 - 511 > 0 ? t0 - 511 : 0) >> 6, w_hi = t0 >> 6;
;     f32x4 oc[4] = {z4, z4, z4, z4};
;     const int tl = t0 + 3, nvmax = tl >= 31 ? ((tl - 31) >> 4) + 1 : 0, ngr = (nvmax + 63) >> 6;
;     if (ngr > 0) {
;     ...
;     for (int tt = 0; tt < 4; ++tt) { const float gc = GN[(size_t)(b * SEQ + t0 + tt) * 48 + (g * 4 + q4) * 3];
.Ltopk_done_q0:
	s_nop 0
	s_waitcnt lgkmcnt(0)
	s_lshl_b32 s47, s18, 6
	s_add_i32 s47, s47, s80
	s_add_i32 s47, s47, 4
	v_and_b32_e32 v232, 15, v184
	v_and_b32_e32 v234, 3, v232
	v_lshrrev_b32_e32 v235, 2, v232
	s_add_i32 s0, s47, s97
	v_add_u32_e32 v253, s0, v234
	s_and_b32 s1, s88, 3
	s_lshl_b32 s1, s1, 2
	v_add_u32_e32 v0, s1, v235
	v_mul_u32_u24_e32 v99, 0xc0, v253
	v_mul_u32_u24_e32 v0, 12, v0
	v_add_u32_e32 v99, v99, v0
	s_add_u32 s72, s30, 0x38310000
	s_addc_u32 s73, s31, 0
	global_load_dword v227, v99, s[72:73]
	v_mov_b32_e32 v2, 0
	v_mov_b32_e32 v3, 0
	v_mov_b32_e32 v4, 0
	v_mov_b32_e32 v5, 0
	v_mov_b32_e32 v6, 0
	v_mov_b32_e32 v7, 0
	v_mov_b32_e32 v8, 0
	v_mov_b32_e32 v9, 0
	v_mov_b32_e32 v10, 0
	v_mov_b32_e32 v11, 0
	v_mov_b32_e32 v12, 0
	v_mov_b32_e32 v13, 0
	v_mov_b32_e32 v14, 0
	v_mov_b32_e32 v15, 0
	v_mov_b32_e32 v16, 0
	v_mov_b32_e32 v17, 0
	s_sub_i32 s0, s47, 28
	s_ashr_i32 s0, s0, 4
	s_add_i32 s0, s0, 64
	s_ashr_i32 s53, s0, 6
	s_cmp_gt_i32 s47, 27
	s_cselect_b32 s53, s53, 0
	s_sub_i32 s0, s47, 2063
	s_ashr_i32 s52, s0, 10
	s_add_i32 s52, s52, 1
	s_max_i32 s52, s52, 0
	s_min_i32 s52, s52, s53
	v_add_u32_e32 v99, s47, v172
	v_and_b32_e32 v98, 15, v184
	v_mov_b32_e32 v170, 0
	s_mov_b32 s57, 0

; #define LAS __attribute__((address_space(3)))
; __device__ __forceinline__ bf16_t tobf(float x) { return (bf16_t)pk2(x, 0.f); }
; __device__ __forceinline__ void nsa_quad_pre(int bg, int quad, const bf16_t* Q, const bf16_t* KV, const bf16_t* KCMP, const bf16_t* VCMPT, const float* GN, bf16_t* ONSA, ...
;     ...
;         for (int gr = 0; gr < ngr; ++gr) {
;             const bool more = gr + 1 < ngr;
;             qk_scores(KF, qf, sc);
;             if (more) load_k(KF, KP_C(gr + 1));
;             cmp_sm2(sc, gr, t0, bt, inv, Pb, psum, r16, q4);
;             pv_step(VF, oc, Pb, r16, q4);
;             if (more) load_v(VF, VP_C(gr + 1));
;         }
;     ...
;             unsigned k0 = 0u, k1 = 0u;
;             { const int j = lane; if (j >= 1 && j <= cur - 2) { const LAS float* ps = psum + tt * 512 + 4 * j - 1; const float v = ps[0] + ps[1] + ps[2] + ps[3] + ps[4]; k0 = (__builtin_bit_cast(unsigned, v) & ~127u) | (unsigned)(127 - j); } }
;             { const int j = lane + 64; if (j <= cur - 2) { const LAS float* ps = psum + tt * 512 + 4 * j - 1; const float v = ps[0] + ps[1] + ps[2] + ps[3] + ps[4]; k1 = (__builtin_bit_cast(unsigned, v) & ~127u) | (unsigned)(127 - j); } }
;             for (int it = 0; it < 13; ++it) {
;                 unsigned m = k0 > k1 ? k0 : k1;
; #pragma unroll
;                 for (int off = 32; off >= 1; off >>= 1) { const unsigned o = (unsigned)__shfl_xor((int)m, off); m = o > m ? o : m; }
;                 if (k0 == m) k0 = 0u; if (k1 == m) k1 = 0u;
;     ...
;     for (int tt = 0; tt < 4; ++tt) { const float gc = GN[(size_t)(b * SEQ + t0 + tt) * 48 + (g * 4 + q4) * 3];
;         bf16_t* op = ONSA + (size_t)(b * SEQ + t0 + tt) * 1024 + (g * 4 + q4) * 64 + r16;
; #pragma unroll
;         for (int nt = 0; nt < 4; ++nt) op[nt * 16] = tobf(gc * oc[nt][tt]); }
.Lcmp_tail_q1p2:
	s_waitcnt vmcnt(2) lgkmcnt(0)
	s_barrier
	s_add_i32 s75, s75, 1
	s_cmp_eq_u32 s75, 3
	s_cselect_b32 s75, 0, s75
	s_add_i32 s57, s57, 1
	s_cmp_lt_i32 s57, s74
	s_cbranch_scc1 .Lcmp_top_q1p2
	s_waitcnt lgkmcnt(0)
	s_nop 7
	s_nop 3
	v_and_b32_e32 v232, 15, v184
	v_lshrrev_b32_e32 v233, 4, v184
	v_and_b32_e32 v234, 3, v232
	v_lshrrev_b32_e32 v235, 2, v232
	s_add_i32 s0, s47, s97
	v_add_u32_e32 v253, s0, v234
	s_and_b32 s1, s88, 3
	s_lshl_b32 s1, s1, 2
	v_add_u32_e32 v0, s1, v235
	v_lshlrev_b32_e32 v98, 7, v0
	v_lshl_add_u32 v98, v253, 11, v98
	v_lshl_add_u32 v98, v233, 3, v98
	s_add_u32 s14, s30, 0xf900000
	s_addc_u32 s15, s31, 0
	s_waitcnt vmcnt(0)
	v_mul_f32_e32 v2, v2, v227
	v_mul_f32_e32 v3, v3, v227
	v_mul_f32_e32 v4, v4, v227
	v_mul_f32_e32 v5, v5, v227
	v_mul_f32_e32 v6, v6, v227
	v_mul_f32_e32 v7, v7, v227
	v_mul_f32_e32 v8, v8, v227
	v_mul_f32_e32 v9, v9, v227
	v_mul_f32_e32 v10, v10, v227
	v_mul_f32_e32 v11, v11, v227
	v_mul_f32_e32 v12, v12, v227
	v_mul_f32_e32 v13, v13, v227
	v_mul_f32_e32 v14, v14, v227
	v_mul_f32_e32 v15, v15, v227
	v_mul_f32_e32 v16, v16, v227
	v_mul_f32_e32 v17, v17, v227
	v_cvt_pk_bf16_f32 v216, v2, v3
	v_cvt_pk_bf16_f32 v217, v4, v5
	v_cvt_pk_bf16_f32 v218, v6, v7
	v_cvt_pk_bf16_f32 v219, v8, v9
	v_cvt_pk_bf16_f32 v220, v10, v11
	v_cvt_pk_bf16_f32 v221, v12, v13
	v_cvt_pk_bf16_f32 v222, v14, v15
	v_cvt_pk_bf16_f32 v223, v16, v17
	global_store_dwordx2 v98, v[216:217], s[14:15] offset:0
	global_store_dwordx2 v98, v[218:219], s[14:15] offset:32
	global_store_dwordx2 v98, v[220:221], s[14:15] offset:64
	global_store_dwordx2 v98, v[222:223], s[14:15] offset:96
	s_waitcnt lgkmcnt(0)
	s_cmp_gt_i32 s18, 15
	s_cbranch_scc0 .Ltopk_small_q1
	s_lshl_b32 s19, s80, 10
	s_add_i32 s19, s19, 56384
	v_lshlrev_b32_e32 v96, 4, v184
	v_add_u32_e32 v96, s19, v96
	v_add_u32_e32 v97, 0xfffffffc, v96
	v_sub_u32_e32 v94, 127, v184
	v_sub_u32_e32 v95, 63, v184
	s_mov_b32 s54, 0xffffff80
	s_add_i32 s21, s18, -2
	v_add_u32_e32 v236, 64, v184
	ds_read_b32 v86, v97 offset:0
	ds_read_b128 v[50:53], v96 offset:0
	ds_read_b32 v87, v97 offset:1024
	ds_read_b128 v[54:57], v96 offset:1024
	ds_read_b32 v88, v97 offset:2048
	ds_read_b128 v[58:61], v96 offset:2048
	ds_read_b32 v89, v97 offset:3072
	ds_read_b128 v[62:65], v96 offset:3072
	s_waitcnt lgkmcnt(6)
	v_add_f32_e32 v86, v86, v50
	v_add_f32_e32 v86, v86, v51
	v_add_f32_e32 v86, v86, v52
	v_add_f32_e32 v86, v86, v53
	v_and_or_b32 v18, v86, s54, v94
	s_waitcnt lgkmcnt(4)
	v_add_f32_e32 v87, v87, v54
	v_add_f32_e32 v87, v87, v55
	v_add_f32_e32 v87, v87, v56
	v_add_f32_e32 v87, v87, v57
	v_and_or_b32 v22, v87, s54, v95
	s_waitcnt lgkmcnt(2)
	v_add_f32_e32 v88, v88, v58
	v_add_f32_e32 v88, v88, v59
	v_add_f32_e32 v88, v88, v60
	v_add_f32_e32 v88, v88, v61
	v_and_or_b32 v19, v88, s54, v94
	s_waitcnt lgkmcnt(0)
	v_add_f32_e32 v89, v89, v62
	v_add_f32_e32 v89, v89, v63
	v_add_f32_e32 v89, v89, v64
	v_add_f32_e32 v89, v89, v65
	v_and_or_b32 v23, v89, s54, v95
	ds_read_b32 v90, v97 offset:4096
	ds_read_b128 v[66:69], v96 offset:4096
	ds_read_b32 v91, v97 offset:5120
	ds_read_b128 v[70:73], v96 offset:5120
	ds_read_b32 v92, v97 offset:6144
	ds_read_b128 v[74:77], v96 offset:6144
	ds_read_b32 v93, v97 offset:7168
	ds_read_b128 v[78:81], v96 offset:7168
	s_waitcnt lgkmcnt(6)
	v_add_f32_e32 v90, v90, v66
	v_add_f32_e32 v90, v90, v67
	v_add_f32_e32 v90, v90, v68
	v_add_f32_e32 v90, v90, v69
	v_and_or_b32 v20, v90, s54, v94
	s_waitcnt lgkmcnt(4)
	v_add_f32_e32 v91, v91, v70
	v_add_f32_e32 v91, v91, v71
	v_add_f32_e32 v91, v91, v72
	v_add_f32_e32 v91, v91, v73
	v_and_or_b32 v24, v91, s54, v95
	s_waitcnt lgkmcnt(2)
	v_add_f32_e32 v92, v92, v74
	v_add_f32_e32 v92, v92, v75
	v_add_f32_e32 v92, v92, v76
	v_add_f32_e32 v92, v92, v77
	v_and_or_b32 v21, v92, s54, v94
	s_waitcnt lgkmcnt(0)
	v_add_f32_e32 v93, v93, v78
	v_add_f32_e32 v93, v93, v79
	v_add_f32_e32 v93, v93, v80
	v_add_f32_e32 v93, v93, v81
	v_and_or_b32 v25, v93, s54, v95
	v_cmp_le_i32_e64 s[14:15], v184, s21
	v_cmp_lt_i32_e64 s[34:35], 0, v184
	s_nop 0
	s_and_b64 s[14:15], s[14:15], s[34:35]
	v_cmp_le_i32_e64 s[34:35], v236, s21
	v_cndmask_b32_e64 v18, 0, v18, s[14:15]
	s_nop 0
	v_cndmask_b32_e64 v22, 0, v22, s[34:35]
	v_mov_b32_e32 v82, 127
	v_cndmask_b32_e64 v19, 0, v19, s[14:15]
	v_cndmask_b32_e64 v23, 0, v23, s[34:35]
	v_mov_b32_e32 v83, 127
	v_cndmask_b32_e64 v20, 0, v20, s[14:15]
	v_cndmask_b32_e64 v24, 0, v24, s[34:35]
	v_mov_b32_e32 v84, 127
	v_cndmask_b32_e64 v21, 0, v21, s[14:15]
	v_cndmask_b32_e64 v25, 0, v25, s[34:35]
	v_mov_b32_e32 v85, 127
	v_max_u32_e32 v26, v18, v22
	v_max_u32_e32 v27, v19, v23
	v_max_u32_e32 v28, v20, v24
	v_max_u32_e32 v29, v21, v25
	v_max_u32_dpp v26, v26, v26 quad_perm:[1,0,3,2] row_mask:0xf bank_mask:0xf
	v_max_u32_dpp v27, v27, v27 quad_perm:[1,0,3,2] row_mask:0xf bank_mask:0xf
	v_max_u32_dpp v28, v28, v28 quad_perm:[1,0,3,2] row_mask:0xf bank_mask:0xf
	v_max_u32_dpp v29, v29, v29 quad_perm:[1,0,3,2] row_mask:0xf bank_mask:0xf
	v_max_u32_dpp v26, v26, v26 quad_perm:[2,3,0,1] row_mask:0xf bank_mask:0xf
	v_max_u32_dpp v27, v27, v27 quad_perm:[2,3,0,1] row_mask:0xf bank_mask:0xf
	v_max_u32_dpp v28, v28, v28 quad_perm:[2,3,0,1] row_mask:0xf bank_mask:0xf
	v_max_u32_dpp v29, v29, v29 quad_perm:[2,3,0,1] row_mask:0xf bank_mask:0xf
	v_max_u32_dpp v26, v26, v26 row_half_mirror row_mask:0xf bank_mask:0xf
	v_max_u32_dpp v27, v27, v27 row_half_mirror row_mask:0xf bank_mask:0xf
	v_max_u32_dpp v28, v28, v28 row_half_mirror row_mask:0xf bank_mask:0xf
	v_max_u32_dpp v29, v29, v29 row_half_mirror row_mask:0xf bank_mask:0xf
	v_max_u32_dpp v26, v26, v26 row_mirror row_mask:0xf bank_mask:0xf
; __device__ __forceinline__ void nsa_quad_pre(int bg, int quad, const bf16_t* Q, const bf16_t* KV, const bf16_t* KCMP, const bf16_t* VCMPT, const float* GN, bf16_t* ONSA, ...
;     ...
;             for (int it = 0; it < 13; ++it) {
;                 unsigned m = k0 > k1 ? k0 : k1;
; #pragma unroll
;                 for (int off = 32; off >= 1; off >>= 1) { const unsigned o = (unsigned)__shfl_xor((int)m, off); m = o > m ? o : m; }
;                 if (k0 == m) k0 = 0u; if (k1 == m) k1 = 0u;
;                 if (lane == 0) selq[tt * 16 + it] = 127 - (int)(m & 127u);
	v_max_u32_dpp v27, v27, v27 row_mirror row_mask:0xf bank_mask:0xf
	v_max_u32_dpp v28, v28, v28 row_mirror row_mask:0xf bank_mask:0xf
	v_max_u32_dpp v29, v29, v29 row_mirror row_mask:0xf bank_mask:0xf
	v_max_u32_dpp v26, v26, v26 row_bcast:15 row_mask:0xa bank_mask:0xf
	v_max_u32_dpp v27, v27, v27 row_bcast:15 row_mask:0xa bank_mask:0xf
	v_max_u32_dpp v28, v28, v28 row_bcast:15 row_mask:0xa bank_mask:0xf
	v_max_u32_dpp v29, v29, v29 row_bcast:15 row_mask:0xa bank_mask:0xf
	v_max_u32_dpp v26, v26, v26 row_bcast:31 row_mask:0xc bank_mask:0xf
	v_max_u32_dpp v27, v27, v27 row_bcast:31 row_mask:0xc bank_mask:0xf
	v_max_u32_dpp v28, v28, v28 row_bcast:31 row_mask:0xc bank_mask:0xf
	v_max_u32_dpp v29, v29, v29 row_bcast:31 row_mask:0xc bank_mask:0xf
	v_readlane_b32 s14, v26, 63
	v_readlane_b32 s15, v27, 63
	v_readlane_b32 s34, v28, 63
	v_readlane_b32 s35, v29, 63
	v_writelane_b32 v82, s14, 0
	v_writelane_b32 v83, s15, 0
	v_writelane_b32 v84, s34, 0
	v_writelane_b32 v85, s35, 0
	v_cmp_ne_u32_e64 s[42:43], s14, v18
	v_cmp_ne_u32_e64 s[66:67], s14, v22
	v_cmp_ne_u32_e64 s[0:1], s15, v19
	v_cmp_ne_u32_e32 vcc, s15, v23
	v_cndmask_b32_e64 v18, 0, v18, s[42:43]
	v_cndmask_b32_e64 v22, 0, v22, s[66:67]
	v_cndmask_b32_e64 v19, 0, v19, s[0:1]
	v_cndmask_b32_e32 v23, 0, v23, vcc
	v_cmp_ne_u32_e64 s[42:43], s34, v20
	v_cmp_ne_u32_e64 s[66:67], s34, v24
	v_cmp_ne_u32_e64 s[0:1], s35, v21
	v_cmp_ne_u32_e32 vcc, s35, v25
	v_cndmask_b32_e64 v20, 0, v20, s[42:43]
	v_cndmask_b32_e64 v24, 0, v24, s[66:67]
	v_cndmask_b32_e64 v21, 0, v21, s[0:1]
	v_cndmask_b32_e32 v25, 0, v25, vcc
	v_max_u32_e32 v26, v18, v22
	v_max_u32_e32 v27, v19, v23
	v_max_u32_e32 v28, v20, v24
	v_max_u32_e32 v29, v21, v25
	v_max_u32_dpp v26, v26, v26 quad_perm:[1,0,3,2] row_mask:0xf bank_mask:0xf
	v_max_u32_dpp v27, v27, v27 quad_perm:[1,0,3,2] row_mask:0xf bank_mask:0xf
	v_max_u32_dpp v28, v28, v28 quad_perm:[1,0,3,2] row_mask:0xf bank_mask:0xf
	v_max_u32_dpp v29, v29, v29 quad_perm:[1,0,3,2] row_mask:0xf bank_mask:0xf
	v_max_u32_dpp v26, v26, v26 quad_perm:[2,3,0,1] row_mask:0xf bank_mask:0xf
	v_max_u32_dpp v27, v27, v27 quad_perm:[2,3,0,1] row_mask:0xf bank_mask:0xf
	v_max_u32_dpp v28, v28, v28 quad_perm:[2,3,0,1] row_mask:0xf bank_mask:0xf
	v_max_u32_dpp v29, v29, v29 quad_perm:[2,3,0,1] row_mask:0xf bank_mask:0xf
	v_max_u32_dpp v26, v26, v26 row_half_mirror row_mask:0xf bank_mask:0xf
	v_max_u32_dpp v27, v27, v27 row_half_mirror row_mask:0xf bank_mask:0xf
	v_max_u32_dpp v28, v28, v28 row_half_mirror row_mask:0xf bank_mask:0xf
	v_max_u32_dpp v29, v29, v29 row_half_mirror row_mask:0xf bank_mask:0xf
	v_max_u32_dpp v26, v26, v26 row_mirror row_mask:0xf bank_mask:0xf
	v_max_u32_dpp v27, v27, v27 row_mirror row_mask:0xf bank_mask:0xf
	v_max_u32_dpp v28, v28, v28 row_mirror row_mask:0xf bank_mask:0xf
	v_max_u32_dpp v29, v29, v29 row_mirror row_mask:0xf bank_mask:0xf
	v_max_u32_dpp v26, v26, v26 row_bcast:15 row_mask:0xa bank_mask:0xf
	v_max_u32_dpp v27, v27, v27 row_bcast:15 row_mask:0xa bank_mask:0xf
	v_max_u32_dpp v28, v28, v28 row_bcast:15 row_mask:0xa bank_mask:0xf
	v_max_u32_dpp v29, v29, v29 row_bcast:15 row_mask:0xa bank_mask:0xf
	v_max_u32_dpp v26, v26, v26 row_bcast:31 row_mask:0xc bank_mask:0xf
	v_max_u32_dpp v27, v27, v27 row_bcast:31 row_mask:0xc bank_mask:0xf
	v_max_u32_dpp v28, v28, v28 row_bcast:31 row_mask:0xc bank_mask:0xf
	v_max_u32_dpp v29, v29, v29 row_bcast:31 row_mask:0xc bank_mask:0xf
	v_readlane_b32 s14, v26, 63
	v_readlane_b32 s15, v27, 63
	v_readlane_b32 s34, v28, 63
	v_readlane_b32 s35, v29, 63
	v_writelane_b32 v82, s14, 1
	v_writelane_b32 v83, s15, 1
	v_writelane_b32 v84, s34, 1
	v_writelane_b32 v85, s35, 1
	v_cmp_ne_u32_e64 s[42:43], s14, v18
	v_cmp_ne_u32_e64 s[66:67], s14, v22
	v_cmp_ne_u32_e64 s[0:1], s15, v19
	v_cmp_ne_u32_e32 vcc, s15, v23
	v_cndmask_b32_e64 v18, 0, v18, s[42:43]
	v_cndmask_b32_e64 v22, 0, v22, s[66:67]
	v_cndmask_b32_e64 v19, 0, v19, s[0:1]
	v_cndmask_b32_e32 v23, 0, v23, vcc
	v_cmp_ne_u32_e64 s[42:43], s34, v20
	v_cmp_ne_u32_e64 s[66:67], s34, v24
	v_cmp_ne_u32_e64 s[0:1], s35, v21
	v_cmp_ne_u32_e32 vcc, s35, v25
	v_cndmask_b32_e64 v20, 0, v20, s[42:43]
	v_cndmask_b32_e64 v24, 0, v24, s[66:67]
	v_cndmask_b32_e64 v21, 0, v21, s[0:1]
	v_cndmask_b32_e32 v25, 0, v25, vcc
	v_max_u32_e32 v26, v18, v22
	v_max_u32_e32 v27, v19, v23
	v_max_u32_e32 v28, v20, v24
	v_max_u32_e32 v29, v21, v25
	v_max_u32_dpp v26, v26, v26 quad_perm:[1,0,3,2] row_mask:0xf bank_mask:0xf
	v_max_u32_dpp v27, v27, v27 quad_perm:[1,0,3,2] row_mask:0xf bank_mask:0xf
	v_max_u32_dpp v28, v28, v28 quad_perm:[1,0,3,2] row_mask:0xf bank_mask:0xf
	v_max_u32_dpp v29, v29, v29 quad_perm:[1,0,3,2] row_mask:0xf bank_mask:0xf
	v_max_u32_dpp v26, v26, v26 quad_perm:[2,3,0,1] row_mask:0xf bank_mask:0xf
	v_max_u32_dpp v27, v27, v27 quad_perm:[2,3,0,1] row_mask:0xf bank_mask:0xf
	v_max_u32_dpp v28, v28, v28 quad_perm:[2,3,0,1] row_mask:0xf bank_mask:0xf
	v_max_u32_dpp v29, v29, v29 quad_perm:[2,3,0,1] row_mask:0xf bank_mask:0xf
	v_max_u32_dpp v26, v26, v26 row_half_mirror row_mask:0xf bank_mask:0xf
	v_max_u32_dpp v27, v27, v27 row_half_mirror row_mask:0xf bank_mask:0xf
	v_max_u32_dpp v28, v28, v28 row_half_mirror row_mask:0xf bank_mask:0xf
	v_max_u32_dpp v29, v29, v29 row_half_mirror row_mask:0xf bank_mask:0xf
	v_max_u32_dpp v26, v26, v26 row_mirror row_mask:0xf bank_mask:0xf
	v_max_u32_dpp v27, v27, v27 row_mirror row_mask:0xf bank_mask:0xf
	v_max_u32_dpp v28, v28, v28 row_mirror row_mask:0xf bank_mask:0xf
	v_max_u32_dpp v29, v29, v29 row_mirror row_mask:0xf bank_mask:0xf
	v_max_u32_dpp v26, v26, v26 row_bcast:15 row_mask:0xa bank_mask:0xf
	v_max_u32_dpp v27, v27, v27 row_bcast:15 row_mask:0xa bank_mask:0xf
; __device__ __forceinline__ void nsa_quad_pre(int bg, int quad, const bf16_t* Q, const bf16_t* KV, const bf16_t* KCMP, const bf16_t* VCMPT, const float* GN, bf16_t* ONSA, ...
;     ...
;             for (int it = 0; it < 13; ++it) {
;                 unsigned m = k0 > k1 ? k0 : k1;
; #pragma unroll
;                 for (int off = 32; off >= 1; off >>= 1) { const unsigned o = (unsigned)__shfl_xor((int)m, off); m = o > m ? o : m; }
;                 if (k0 == m) k0 = 0u; if (k1 == m) k1 = 0u;
;                 if (lane == 0) selq[tt * 16 + it] = 127 - (int)(m & 127u);
	v_max_u32_dpp v28, v28, v28 row_bcast:15 row_mask:0xa bank_mask:0xf
	v_max_u32_dpp v29, v29, v29 row_bcast:15 row_mask:0xa bank_mask:0xf
	v_max_u32_dpp v26, v26, v26 row_bcast:31 row_mask:0xc bank_mask:0xf
	v_max_u32_dpp v27, v27, v27 row_bcast:31 row_mask:0xc bank_mask:0xf
	v_max_u32_dpp v28, v28, v28 row_bcast:31 row_mask:0xc bank_mask:0xf
	v_max_u32_dpp v29, v29, v29 row_bcast:31 row_mask:0xc bank_mask:0xf
	v_readlane_b32 s14, v26, 63
	v_readlane_b32 s15, v27, 63
	v_readlane_b32 s34, v28, 63
	v_readlane_b32 s35, v29, 63
	v_writelane_b32 v82, s14, 2
	v_writelane_b32 v83, s15, 2
	v_writelane_b32 v84, s34, 2
	v_writelane_b32 v85, s35, 2
	v_cmp_ne_u32_e64 s[42:43], s14, v18
	v_cmp_ne_u32_e64 s[66:67], s14, v22
	v_cmp_ne_u32_e64 s[0:1], s15, v19
	v_cmp_ne_u32_e32 vcc, s15, v23
	v_cndmask_b32_e64 v18, 0, v18, s[42:43]
	v_cndmask_b32_e64 v22, 0, v22, s[66:67]
	v_cndmask_b32_e64 v19, 0, v19, s[0:1]
	v_cndmask_b32_e32 v23, 0, v23, vcc
	v_cmp_ne_u32_e64 s[42:43], s34, v20
	v_cmp_ne_u32_e64 s[66:67], s34, v24
	v_cmp_ne_u32_e64 s[0:1], s35, v21
	v_cmp_ne_u32_e32 vcc, s35, v25
	v_cndmask_b32_e64 v20, 0, v20, s[42:43]
	v_cndmask_b32_e64 v24, 0, v24, s[66:67]
	v_cndmask_b32_e64 v21, 0, v21, s[0:1]
	v_cndmask_b32_e32 v25, 0, v25, vcc
	v_max_u32_e32 v26, v18, v22
	v_max_u32_e32 v27, v19, v23
	v_max_u32_e32 v28, v20, v24
	v_max_u32_e32 v29, v21, v25
	v_max_u32_dpp v26, v26, v26 quad_perm:[1,0,3,2] row_mask:0xf bank_mask:0xf
	v_max_u32_dpp v27, v27, v27 quad_perm:[1,0,3,2] row_mask:0xf bank_mask:0xf
	v_max_u32_dpp v28, v28, v28 quad_perm:[1,0,3,2] row_mask:0xf bank_mask:0xf
	v_max_u32_dpp v29, v29, v29 quad_perm:[1,0,3,2] row_mask:0xf bank_mask:0xf
	v_max_u32_dpp v26, v26, v26 quad_perm:[2,3,0,1] row_mask:0xf bank_mask:0xf
	v_max_u32_dpp v27, v27, v27 quad_perm:[2,3,0,1] row_mask:0xf bank_mask:0xf
	v_max_u32_dpp v28, v28, v28 quad_perm:[2,3,0,1] row_mask:0xf bank_mask:0xf
	v_max_u32_dpp v29, v29, v29 quad_perm:[2,3,0,1] row_mask:0xf bank_mask:0xf
	v_max_u32_dpp v26, v26, v26 row_half_mirror row_mask:0xf bank_mask:0xf
	v_max_u32_dpp v27, v27, v27 row_half_mirror row_mask:0xf bank_mask:0xf
	v_max_u32_dpp v28, v28, v28 row_half_mirror row_mask:0xf bank_mask:0xf
	v_max_u32_dpp v29, v29, v29 row_half_mirror row_mask:0xf bank_mask:0xf
	v_max_u32_dpp v26, v26, v26 row_mirror row_mask:0xf bank_mask:0xf
	v_max_u32_dpp v27, v27, v27 row_mirror row_mask:0xf bank_mask:0xf
	v_max_u32_dpp v28, v28, v28 row_mirror row_mask:0xf bank_mask:0xf
	v_max_u32_dpp v29, v29, v29 row_mirror row_mask:0xf bank_mask:0xf
	v_max_u32_dpp v26, v26, v26 row_bcast:15 row_mask:0xa bank_mask:0xf
	v_max_u32_dpp v27, v27, v27 row_bcast:15 row_mask:0xa bank_mask:0xf
	v_max_u32_dpp v28, v28, v28 row_bcast:15 row_mask:0xa bank_mask:0xf
	v_max_u32_dpp v29, v29, v29 row_bcast:15 row_mask:0xa bank_mask:0xf
	v_max_u32_dpp v26, v26, v26 row_bcast:31 row_mask:0xc bank_mask:0xf
	v_max_u32_dpp v27, v27, v27 row_bcast:31 row_mask:0xc bank_mask:0xf
	v_max_u32_dpp v28, v28, v28 row_bcast:31 row_mask:0xc bank_mask:0xf
	v_max_u32_dpp v29, v29, v29 row_bcast:31 row_mask:0xc bank_mask:0xf
	v_readlane_b32 s14, v26, 63
	v_readlane_b32 s15, v27, 63
	v_readlane_b32 s34, v28, 63
	v_readlane_b32 s35, v29, 63
	v_writelane_b32 v82, s14, 3
	v_writelane_b32 v83, s15, 3
	v_writelane_b32 v84, s34, 3
	v_writelane_b32 v85, s35, 3
	v_cmp_ne_u32_e64 s[42:43], s14, v18
	v_cmp_ne_u32_e64 s[66:67], s14, v22
	v_cmp_ne_u32_e64 s[0:1], s15, v19
	v_cmp_ne_u32_e32 vcc, s15, v23
	v_cndmask_b32_e64 v18, 0, v18, s[42:43]
	v_cndmask_b32_e64 v22, 0, v22, s[66:67]
	v_cndmask_b32_e64 v19, 0, v19, s[0:1]
	v_cndmask_b32_e32 v23, 0, v23, vcc
	v_cmp_ne_u32_e64 s[42:43], s34, v20
	v_cmp_ne_u32_e64 s[66:67], s34, v24
	v_cmp_ne_u32_e64 s[0:1], s35, v21
	v_cmp_ne_u32_e32 vcc, s35, v25
	v_cndmask_b32_e64 v20, 0, v20, s[42:43]
	v_cndmask_b32_e64 v24, 0, v24, s[66:67]
	v_cndmask_b32_e64 v21, 0, v21, s[0:1]
	v_cndmask_b32_e32 v25, 0, v25, vcc
	v_max_u32_e32 v26, v18, v22
	v_max_u32_e32 v27, v19, v23
	v_max_u32_e32 v28, v20, v24
	v_max_u32_e32 v29, v21, v25
	v_max_u32_dpp v26, v26, v26 quad_perm:[1,0,3,2] row_mask:0xf bank_mask:0xf
	v_max_u32_dpp v27, v27, v27 quad_perm:[1,0,3,2] row_mask:0xf bank_mask:0xf
	v_max_u32_dpp v28, v28, v28 quad_perm:[1,0,3,2] row_mask:0xf bank_mask:0xf
	v_max_u32_dpp v29, v29, v29 quad_perm:[1,0,3,2] row_mask:0xf bank_mask:0xf
	v_max_u32_dpp v26, v26, v26 quad_perm:[2,3,0,1] row_mask:0xf bank_mask:0xf
	v_max_u32_dpp v27, v27, v27 quad_perm:[2,3,0,1] row_mask:0xf bank_mask:0xf
	v_max_u32_dpp v28, v28, v28 quad_perm:[2,3,0,1] row_mask:0xf bank_mask:0xf
	v_max_u32_dpp v29, v29, v29 quad_perm:[2,3,0,1] row_mask:0xf bank_mask:0xf
	v_max_u32_dpp v26, v26, v26 row_half_mirror row_mask:0xf bank_mask:0xf
	v_max_u32_dpp v27, v27, v27 row_half_mirror row_mask:0xf bank_mask:0xf
	v_max_u32_dpp v28, v28, v28 row_half_mirror row_mask:0xf bank_mask:0xf
	v_max_u32_dpp v29, v29, v29 row_half_mirror row_mask:0xf bank_mask:0xf
	v_max_u32_dpp v26, v26, v26 row_mirror row_mask:0xf bank_mask:0xf
	v_max_u32_dpp v27, v27, v27 row_mirror row_mask:0xf bank_mask:0xf
	v_max_u32_dpp v28, v28, v28 row_mirror row_mask:0xf bank_mask:0xf
	v_max_u32_dpp v29, v29, v29 row_mirror row_mask:0xf bank_mask:0xf
	v_max_u32_dpp v26, v26, v26 row_bcast:15 row_mask:0xa bank_mask:0xf
	v_max_u32_dpp v27, v27, v27 row_bcast:15 row_mask:0xa bank_mask:0xf
	v_max_u32_dpp v28, v28, v28 row_bcast:15 row_mask:0xa bank_mask:0xf
	v_max_u32_dpp v29, v29, v29 row_bcast:15 row_mask:0xa bank_mask:0xf
	v_max_u32_dpp v26, v26, v26 row_bcast:31 row_mask:0xc bank_mask:0xf
	v_max_u32_dpp v27, v27, v27 row_bcast:31 row_mask:0xc bank_mask:0xf
	v_max_u32_dpp v28, v28, v28 row_bcast:31 row_mask:0xc bank_mask:0xf
; __device__ __forceinline__ void nsa_quad_pre(int bg, int quad, const bf16_t* Q, const bf16_t* KV, const bf16_t* KCMP, const bf16_t* VCMPT, const float* GN, bf16_t* ONSA, ...
;     ...
;             for (int it = 0; it < 13; ++it) {
;                 unsigned m = k0 > k1 ? k0 : k1;
; #pragma unroll
;                 for (int off = 32; off >= 1; off >>= 1) { const unsigned o = (unsigned)__shfl_xor((int)m, off); m = o > m ? o : m; }
;                 if (k0 == m) k0 = 0u; if (k1 == m) k1 = 0u;
;                 if (lane == 0) selq[tt * 16 + it] = 127 - (int)(m & 127u);
	v_max_u32_dpp v29, v29, v29 row_bcast:31 row_mask:0xc bank_mask:0xf
	v_readlane_b32 s14, v26, 63
	v_readlane_b32 s15, v27, 63
	v_readlane_b32 s34, v28, 63
	v_readlane_b32 s35, v29, 63
	v_writelane_b32 v82, s14, 4
	v_writelane_b32 v83, s15, 4
	v_writelane_b32 v84, s34, 4
	v_writelane_b32 v85, s35, 4
	v_cmp_ne_u32_e64 s[42:43], s14, v18
	v_cmp_ne_u32_e64 s[66:67], s14, v22
	v_cmp_ne_u32_e64 s[0:1], s15, v19
	v_cmp_ne_u32_e32 vcc, s15, v23
	v_cndmask_b32_e64 v18, 0, v18, s[42:43]
	v_cndmask_b32_e64 v22, 0, v22, s[66:67]
	v_cndmask_b32_e64 v19, 0, v19, s[0:1]
	v_cndmask_b32_e32 v23, 0, v23, vcc
	v_cmp_ne_u32_e64 s[42:43], s34, v20
	v_cmp_ne_u32_e64 s[66:67], s34, v24
	v_cmp_ne_u32_e64 s[0:1], s35, v21
	v_cmp_ne_u32_e32 vcc, s35, v25
	v_cndmask_b32_e64 v20, 0, v20, s[42:43]
	v_cndmask_b32_e64 v24, 0, v24, s[66:67]
	v_cndmask_b32_e64 v21, 0, v21, s[0:1]
	v_cndmask_b32_e32 v25, 0, v25, vcc
	v_max_u32_e32 v26, v18, v22
	v_max_u32_e32 v27, v19, v23
	v_max_u32_e32 v28, v20, v24
	v_max_u32_e32 v29, v21, v25
	v_max_u32_dpp v26, v26, v26 quad_perm:[1,0,3,2] row_mask:0xf bank_mask:0xf
	v_max_u32_dpp v27, v27, v27 quad_perm:[1,0,3,2] row_mask:0xf bank_mask:0xf
	v_max_u32_dpp v28, v28, v28 quad_perm:[1,0,3,2] row_mask:0xf bank_mask:0xf
	v_max_u32_dpp v29, v29, v29 quad_perm:[1,0,3,2] row_mask:0xf bank_mask:0xf
	v_max_u32_dpp v26, v26, v26 quad_perm:[2,3,0,1] row_mask:0xf bank_mask:0xf
	v_max_u32_dpp v27, v27, v27 quad_perm:[2,3,0,1] row_mask:0xf bank_mask:0xf
	v_max_u32_dpp v28, v28, v28 quad_perm:[2,3,0,1] row_mask:0xf bank_mask:0xf
	v_max_u32_dpp v29, v29, v29 quad_perm:[2,3,0,1] row_mask:0xf bank_mask:0xf
	v_max_u32_dpp v26, v26, v26 row_half_mirror row_mask:0xf bank_mask:0xf
	v_max_u32_dpp v27, v27, v27 row_half_mirror row_mask:0xf bank_mask:0xf
	v_max_u32_dpp v28, v28, v28 row_half_mirror row_mask:0xf bank_mask:0xf
	v_max_u32_dpp v29, v29, v29 row_half_mirror row_mask:0xf bank_mask:0xf
	v_max_u32_dpp v26, v26, v26 row_mirror row_mask:0xf bank_mask:0xf
	v_max_u32_dpp v27, v27, v27 row_mirror row_mask:0xf bank_mask:0xf
	v_max_u32_dpp v28, v28, v28 row_mirror row_mask:0xf bank_mask:0xf
	v_max_u32_dpp v29, v29, v29 row_mirror row_mask:0xf bank_mask:0xf
	v_max_u32_dpp v26, v26, v26 row_bcast:15 row_mask:0xa bank_mask:0xf
	v_max_u32_dpp v27, v27, v27 row_bcast:15 row_mask:0xa bank_mask:0xf
	v_max_u32_dpp v28, v28, v28 row_bcast:15 row_mask:0xa bank_mask:0xf
	v_max_u32_dpp v29, v29, v29 row_bcast:15 row_mask:0xa bank_mask:0xf
	v_max_u32_dpp v26, v26, v26 row_bcast:31 row_mask:0xc bank_mask:0xf
	v_max_u32_dpp v27, v27, v27 row_bcast:31 row_mask:0xc bank_mask:0xf
	v_max_u32_dpp v28, v28, v28 row_bcast:31 row_mask:0xc bank_mask:0xf
	v_max_u32_dpp v29, v29, v29 row_bcast:31 row_mask:0xc bank_mask:0xf
	v_readlane_b32 s14, v26, 63
	v_readlane_b32 s15, v27, 63
	v_readlane_b32 s34, v28, 63
	v_readlane_b32 s35, v29, 63
	v_writelane_b32 v82, s14, 5
	v_writelane_b32 v83, s15, 5
	v_writelane_b32 v84, s34, 5
	v_writelane_b32 v85, s35, 5
	v_cmp_ne_u32_e64 s[42:43], s14, v18
	v_cmp_ne_u32_e64 s[66:67], s14, v22
	v_cmp_ne_u32_e64 s[0:1], s15, v19
	v_cmp_ne_u32_e32 vcc, s15, v23
	v_cndmask_b32_e64 v18, 0, v18, s[42:43]
	v_cndmask_b32_e64 v22, 0, v22, s[66:67]
	v_cndmask_b32_e64 v19, 0, v19, s[0:1]
	v_cndmask_b32_e32 v23, 0, v23, vcc
	v_cmp_ne_u32_e64 s[42:43], s34, v20
	v_cmp_ne_u32_e64 s[66:67], s34, v24
	v_cmp_ne_u32_e64 s[0:1], s35, v21
	v_cmp_ne_u32_e32 vcc, s35, v25
	v_cndmask_b32_e64 v20, 0, v20, s[42:43]
	v_cndmask_b32_e64 v24, 0, v24, s[66:67]
	v_cndmask_b32_e64 v21, 0, v21, s[0:1]
	v_cndmask_b32_e32 v25, 0, v25, vcc
	v_max_u32_e32 v26, v18, v22
	v_max_u32_e32 v27, v19, v23
	v_max_u32_e32 v28, v20, v24
	v_max_u32_e32 v29, v21, v25
	v_max_u32_dpp v26, v26, v26 quad_perm:[1,0,3,2] row_mask:0xf bank_mask:0xf
	v_max_u32_dpp v27, v27, v27 quad_perm:[1,0,3,2] row_mask:0xf bank_mask:0xf
	v_max_u32_dpp v28, v28, v28 quad_perm:[1,0,3,2] row_mask:0xf bank_mask:0xf
	v_max_u32_dpp v29, v29, v29 quad_perm:[1,0,3,2] row_mask:0xf bank_mask:0xf
	v_max_u32_dpp v26, v26, v26 quad_perm:[2,3,0,1] row_mask:0xf bank_mask:0xf
	v_max_u32_dpp v27, v27, v27 quad_perm:[2,3,0,1] row_mask:0xf bank_mask:0xf
	v_max_u32_dpp v28, v28, v28 quad_perm:[2,3,0,1] row_mask:0xf bank_mask:0xf
	v_max_u32_dpp v29, v29, v29 quad_perm:[2,3,0,1] row_mask:0xf bank_mask:0xf
	v_max_u32_dpp v26, v26, v26 row_half_mirror row_mask:0xf bank_mask:0xf
	v_max_u32_dpp v27, v27, v27 row_half_mirror row_mask:0xf bank_mask:0xf
	v_max_u32_dpp v28, v28, v28 row_half_mirror row_mask:0xf bank_mask:0xf
	v_max_u32_dpp v29, v29, v29 row_half_mirror row_mask:0xf bank_mask:0xf
	v_max_u32_dpp v26, v26, v26 row_mirror row_mask:0xf bank_mask:0xf
	v_max_u32_dpp v27, v27, v27 row_mirror row_mask:0xf bank_mask:0xf
	v_max_u32_dpp v28, v28, v28 row_mirror row_mask:0xf bank_mask:0xf
	v_max_u32_dpp v29, v29, v29 row_mirror row_mask:0xf bank_mask:0xf
	v_max_u32_dpp v26, v26, v26 row_bcast:15 row_mask:0xa bank_mask:0xf
	v_max_u32_dpp v27, v27, v27 row_bcast:15 row_mask:0xa bank_mask:0xf
	v_max_u32_dpp v28, v28, v28 row_bcast:15 row_mask:0xa bank_mask:0xf
	v_max_u32_dpp v29, v29, v29 row_bcast:15 row_mask:0xa bank_mask:0xf
	v_max_u32_dpp v26, v26, v26 row_bcast:31 row_mask:0xc bank_mask:0xf
	v_max_u32_dpp v27, v27, v27 row_bcast:31 row_mask:0xc bank_mask:0xf
	v_max_u32_dpp v28, v28, v28 row_bcast:31 row_mask:0xc bank_mask:0xf
	v_max_u32_dpp v29, v29, v29 row_bcast:31 row_mask:0xc bank_mask:0xf
	v_readlane_b32 s14, v26, 63
	v_readlane_b32 s15, v27, 63
	v_readlane_b32 s34, v28, 63
	v_readlane_b32 s35, v29, 63
	v_writelane_b32 v82, s14, 6
	v_writelane_b32 v83, s15, 6
	v_writelane_b32 v84, s34, 6
	v_writelane_b32 v85, s35, 6
	v_cmp_ne_u32_e64 s[42:43], s14, v18
; __device__ __forceinline__ void nsa_quad_pre(int bg, int quad, const bf16_t* Q, const bf16_t* KV, const bf16_t* KCMP, const bf16_t* VCMPT, const float* GN, bf16_t* ONSA, ...
;     ...
;             for (int it = 0; it < 13; ++it) {
;                 unsigned m = k0 > k1 ? k0 : k1;
; #pragma unroll
;                 for (int off = 32; off >= 1; off >>= 1) { const unsigned o = (unsigned)__shfl_xor((int)m, off); m = o > m ? o : m; }
;                 if (k0 == m) k0 = 0u; if (k1 == m) k1 = 0u;
;                 if (lane == 0) selq[tt * 16 + it] = 127 - (int)(m & 127u);
	v_cmp_ne_u32_e64 s[66:67], s14, v22
	v_cmp_ne_u32_e64 s[0:1], s15, v19
	v_cmp_ne_u32_e32 vcc, s15, v23
	v_cndmask_b32_e64 v18, 0, v18, s[42:43]
	v_cndmask_b32_e64 v22, 0, v22, s[66:67]
	v_cndmask_b32_e64 v19, 0, v19, s[0:1]
	v_cndmask_b32_e32 v23, 0, v23, vcc
	v_cmp_ne_u32_e64 s[42:43], s34, v20
	v_cmp_ne_u32_e64 s[66:67], s34, v24
	v_cmp_ne_u32_e64 s[0:1], s35, v21
	v_cmp_ne_u32_e32 vcc, s35, v25
	v_cndmask_b32_e64 v20, 0, v20, s[42:43]
	v_cndmask_b32_e64 v24, 0, v24, s[66:67]
	v_cndmask_b32_e64 v21, 0, v21, s[0:1]
	v_cndmask_b32_e32 v25, 0, v25, vcc
	v_max_u32_e32 v26, v18, v22
	v_max_u32_e32 v27, v19, v23
	v_max_u32_e32 v28, v20, v24
	v_max_u32_e32 v29, v21, v25
	v_max_u32_dpp v26, v26, v26 quad_perm:[1,0,3,2] row_mask:0xf bank_mask:0xf
	v_max_u32_dpp v27, v27, v27 quad_perm:[1,0,3,2] row_mask:0xf bank_mask:0xf
	v_max_u32_dpp v28, v28, v28 quad_perm:[1,0,3,2] row_mask:0xf bank_mask:0xf
	v_max_u32_dpp v29, v29, v29 quad_perm:[1,0,3,2] row_mask:0xf bank_mask:0xf
	v_max_u32_dpp v26, v26, v26 quad_perm:[2,3,0,1] row_mask:0xf bank_mask:0xf
	v_max_u32_dpp v27, v27, v27 quad_perm:[2,3,0,1] row_mask:0xf bank_mask:0xf
	v_max_u32_dpp v28, v28, v28 quad_perm:[2,3,0,1] row_mask:0xf bank_mask:0xf
	v_max_u32_dpp v29, v29, v29 quad_perm:[2,3,0,1] row_mask:0xf bank_mask:0xf
	v_max_u32_dpp v26, v26, v26 row_half_mirror row_mask:0xf bank_mask:0xf
	v_max_u32_dpp v27, v27, v27 row_half_mirror row_mask:0xf bank_mask:0xf
	v_max_u32_dpp v28, v28, v28 row_half_mirror row_mask:0xf bank_mask:0xf
	v_max_u32_dpp v29, v29, v29 row_half_mirror row_mask:0xf bank_mask:0xf
	v_max_u32_dpp v26, v26, v26 row_mirror row_mask:0xf bank_mask:0xf
	v_max_u32_dpp v27, v27, v27 row_mirror row_mask:0xf bank_mask:0xf
	v_max_u32_dpp v28, v28, v28 row_mirror row_mask:0xf bank_mask:0xf
	v_max_u32_dpp v29, v29, v29 row_mirror row_mask:0xf bank_mask:0xf
	v_max_u32_dpp v26, v26, v26 row_bcast:15 row_mask:0xa bank_mask:0xf
	v_max_u32_dpp v27, v27, v27 row_bcast:15 row_mask:0xa bank_mask:0xf
	v_max_u32_dpp v28, v28, v28 row_bcast:15 row_mask:0xa bank_mask:0xf
	v_max_u32_dpp v29, v29, v29 row_bcast:15 row_mask:0xa bank_mask:0xf
	v_max_u32_dpp v26, v26, v26 row_bcast:31 row_mask:0xc bank_mask:0xf
	v_max_u32_dpp v27, v27, v27 row_bcast:31 row_mask:0xc bank_mask:0xf
	v_max_u32_dpp v28, v28, v28 row_bcast:31 row_mask:0xc bank_mask:0xf
	v_max_u32_dpp v29, v29, v29 row_bcast:31 row_mask:0xc bank_mask:0xf
	v_readlane_b32 s14, v26, 63
	v_readlane_b32 s15, v27, 63
	v_readlane_b32 s34, v28, 63
	v_readlane_b32 s35, v29, 63
	v_writelane_b32 v82, s14, 7
	v_writelane_b32 v83, s15, 7
	v_writelane_b32 v84, s34, 7
	v_writelane_b32 v85, s35, 7
	v_cmp_ne_u32_e64 s[42:43], s14, v18
	v_cmp_ne_u32_e64 s[66:67], s14, v22
	v_cmp_ne_u32_e64 s[0:1], s15, v19
	v_cmp_ne_u32_e32 vcc, s15, v23
	v_cndmask_b32_e64 v18, 0, v18, s[42:43]
	v_cndmask_b32_e64 v22, 0, v22, s[66:67]
	v_cndmask_b32_e64 v19, 0, v19, s[0:1]
	v_cndmask_b32_e32 v23, 0, v23, vcc
	v_cmp_ne_u32_e64 s[42:43], s34, v20
	v_cmp_ne_u32_e64 s[66:67], s34, v24
	v_cmp_ne_u32_e64 s[0:1], s35, v21
	v_cmp_ne_u32_e32 vcc, s35, v25
	v_cndmask_b32_e64 v20, 0, v20, s[42:43]
	v_cndmask_b32_e64 v24, 0, v24, s[66:67]
	v_cndmask_b32_e64 v21, 0, v21, s[0:1]
	v_cndmask_b32_e32 v25, 0, v25, vcc
	v_max_u32_e32 v26, v18, v22
	v_max_u32_e32 v27, v19, v23
	v_max_u32_e32 v28, v20, v24
	v_max_u32_e32 v29, v21, v25
	v_max_u32_dpp v26, v26, v26 quad_perm:[1,0,3,2] row_mask:0xf bank_mask:0xf
	v_max_u32_dpp v27, v27, v27 quad_perm:[1,0,3,2] row_mask:0xf bank_mask:0xf
	v_max_u32_dpp v28, v28, v28 quad_perm:[1,0,3,2] row_mask:0xf bank_mask:0xf
	v_max_u32_dpp v29, v29, v29 quad_perm:[1,0,3,2] row_mask:0xf bank_mask:0xf
	v_max_u32_dpp v26, v26, v26 quad_perm:[2,3,0,1] row_mask:0xf bank_mask:0xf
	v_max_u32_dpp v27, v27, v27 quad_perm:[2,3,0,1] row_mask:0xf bank_mask:0xf
	v_max_u32_dpp v28, v28, v28 quad_perm:[2,3,0,1] row_mask:0xf bank_mask:0xf
	v_max_u32_dpp v29, v29, v29 quad_perm:[2,3,0,1] row_mask:0xf bank_mask:0xf
	v_max_u32_dpp v26, v26, v26 row_half_mirror row_mask:0xf bank_mask:0xf
	v_max_u32_dpp v27, v27, v27 row_half_mirror row_mask:0xf bank_mask:0xf
	v_max_u32_dpp v28, v28, v28 row_half_mirror row_mask:0xf bank_mask:0xf
	v_max_u32_dpp v29, v29, v29 row_half_mirror row_mask:0xf bank_mask:0xf
	v_max_u32_dpp v26, v26, v26 row_mirror row_mask:0xf bank_mask:0xf
	v_max_u32_dpp v27, v27, v27 row_mirror row_mask:0xf bank_mask:0xf
	v_max_u32_dpp v28, v28, v28 row_mirror row_mask:0xf bank_mask:0xf
	v_max_u32_dpp v29, v29, v29 row_mirror row_mask:0xf bank_mask:0xf
	v_max_u32_dpp v26, v26, v26 row_bcast:15 row_mask:0xa bank_mask:0xf
	v_max_u32_dpp v27, v27, v27 row_bcast:15 row_mask:0xa bank_mask:0xf
	v_max_u32_dpp v28, v28, v28 row_bcast:15 row_mask:0xa bank_mask:0xf
	v_max_u32_dpp v29, v29, v29 row_bcast:15 row_mask:0xa bank_mask:0xf
	v_max_u32_dpp v26, v26, v26 row_bcast:31 row_mask:0xc bank_mask:0xf
	v_max_u32_dpp v27, v27, v27 row_bcast:31 row_mask:0xc bank_mask:0xf
	v_max_u32_dpp v28, v28, v28 row_bcast:31 row_mask:0xc bank_mask:0xf
	v_max_u32_dpp v29, v29, v29 row_bcast:31 row_mask:0xc bank_mask:0xf
	v_readlane_b32 s14, v26, 63
	v_readlane_b32 s15, v27, 63
	v_readlane_b32 s34, v28, 63
	v_readlane_b32 s35, v29, 63
	v_writelane_b32 v82, s14, 8
	v_writelane_b32 v83, s15, 8
	v_writelane_b32 v84, s34, 8
	v_writelane_b32 v85, s35, 8
	v_cmp_ne_u32_e64 s[42:43], s14, v18
	v_cmp_ne_u32_e64 s[66:67], s14, v22
	v_cmp_ne_u32_e64 s[0:1], s15, v19
	v_cmp_ne_u32_e32 vcc, s15, v23
	v_cndmask_b32_e64 v18, 0, v18, s[42:43]
	v_cndmask_b32_e64 v22, 0, v22, s[66:67]
	v_cndmask_b32_e64 v19, 0, v19, s[0:1]
	v_cndmask_b32_e32 v23, 0, v23, vcc
	v_cmp_ne_u32_e64 s[42:43], s34, v20
	v_cmp_ne_u32_e64 s[66:67], s34, v24
; __device__ __forceinline__ void nsa_quad_pre(int bg, int quad, const bf16_t* Q, const bf16_t* KV, const bf16_t* KCMP, const bf16_t* VCMPT, const float* GN, bf16_t* ONSA, ...
;     ...
;             for (int it = 0; it < 13; ++it) {
;                 unsigned m = k0 > k1 ? k0 : k1;
; #pragma unroll
;                 for (int off = 32; off >= 1; off >>= 1) { const unsigned o = (unsigned)__shfl_xor((int)m, off); m = o > m ? o : m; }
;                 if (k0 == m) k0 = 0u; if (k1 == m) k1 = 0u;
;                 if (lane == 0) selq[tt * 16 + it] = 127 - (int)(m & 127u);
	v_cmp_ne_u32_e64 s[0:1], s35, v21
	v_cmp_ne_u32_e32 vcc, s35, v25
	v_cndmask_b32_e64 v20, 0, v20, s[42:43]
	v_cndmask_b32_e64 v24, 0, v24, s[66:67]
	v_cndmask_b32_e64 v21, 0, v21, s[0:1]
	v_cndmask_b32_e32 v25, 0, v25, vcc
	v_max_u32_e32 v26, v18, v22
	v_max_u32_e32 v27, v19, v23
	v_max_u32_e32 v28, v20, v24
	v_max_u32_e32 v29, v21, v25
	v_max_u32_dpp v26, v26, v26 quad_perm:[1,0,3,2] row_mask:0xf bank_mask:0xf
	v_max_u32_dpp v27, v27, v27 quad_perm:[1,0,3,2] row_mask:0xf bank_mask:0xf
	v_max_u32_dpp v28, v28, v28 quad_perm:[1,0,3,2] row_mask:0xf bank_mask:0xf
	v_max_u32_dpp v29, v29, v29 quad_perm:[1,0,3,2] row_mask:0xf bank_mask:0xf
	v_max_u32_dpp v26, v26, v26 quad_perm:[2,3,0,1] row_mask:0xf bank_mask:0xf
	v_max_u32_dpp v27, v27, v27 quad_perm:[2,3,0,1] row_mask:0xf bank_mask:0xf
	v_max_u32_dpp v28, v28, v28 quad_perm:[2,3,0,1] row_mask:0xf bank_mask:0xf
	v_max_u32_dpp v29, v29, v29 quad_perm:[2,3,0,1] row_mask:0xf bank_mask:0xf
	v_max_u32_dpp v26, v26, v26 row_half_mirror row_mask:0xf bank_mask:0xf
	v_max_u32_dpp v27, v27, v27 row_half_mirror row_mask:0xf bank_mask:0xf
	v_max_u32_dpp v28, v28, v28 row_half_mirror row_mask:0xf bank_mask:0xf
	v_max_u32_dpp v29, v29, v29 row_half_mirror row_mask:0xf bank_mask:0xf
	v_max_u32_dpp v26, v26, v26 row_mirror row_mask:0xf bank_mask:0xf
	v_max_u32_dpp v27, v27, v27 row_mirror row_mask:0xf bank_mask:0xf
	v_max_u32_dpp v28, v28, v28 row_mirror row_mask:0xf bank_mask:0xf
	v_max_u32_dpp v29, v29, v29 row_mirror row_mask:0xf bank_mask:0xf
	v_max_u32_dpp v26, v26, v26 row_bcast:15 row_mask:0xa bank_mask:0xf
	v_max_u32_dpp v27, v27, v27 row_bcast:15 row_mask:0xa bank_mask:0xf
	v_max_u32_dpp v28, v28, v28 row_bcast:15 row_mask:0xa bank_mask:0xf
	v_max_u32_dpp v29, v29, v29 row_bcast:15 row_mask:0xa bank_mask:0xf
	v_max_u32_dpp v26, v26, v26 row_bcast:31 row_mask:0xc bank_mask:0xf
	v_max_u32_dpp v27, v27, v27 row_bcast:31 row_mask:0xc bank_mask:0xf
	v_max_u32_dpp v28, v28, v28 row_bcast:31 row_mask:0xc bank_mask:0xf
	v_max_u32_dpp v29, v29, v29 row_bcast:31 row_mask:0xc bank_mask:0xf
	v_readlane_b32 s14, v26, 63
	v_readlane_b32 s15, v27, 63
	v_readlane_b32 s34, v28, 63
	v_readlane_b32 s35, v29, 63
	v_writelane_b32 v82, s14, 9
	v_writelane_b32 v83, s15, 9
	v_writelane_b32 v84, s34, 9
	v_writelane_b32 v85, s35, 9
	v_cmp_ne_u32_e64 s[42:43], s14, v18
	v_cmp_ne_u32_e64 s[66:67], s14, v22
	v_cmp_ne_u32_e64 s[0:1], s15, v19
	v_cmp_ne_u32_e32 vcc, s15, v23
	v_cndmask_b32_e64 v18, 0, v18, s[42:43]
	v_cndmask_b32_e64 v22, 0, v22, s[66:67]
	v_cndmask_b32_e64 v19, 0, v19, s[0:1]
	v_cndmask_b32_e32 v23, 0, v23, vcc
	v_cmp_ne_u32_e64 s[42:43], s34, v20
	v_cmp_ne_u32_e64 s[66:67], s34, v24
	v_cmp_ne_u32_e64 s[0:1], s35, v21
	v_cmp_ne_u32_e32 vcc, s35, v25
	v_cndmask_b32_e64 v20, 0, v20, s[42:43]
	v_cndmask_b32_e64 v24, 0, v24, s[66:67]
	v_cndmask_b32_e64 v21, 0, v21, s[0:1]
	v_cndmask_b32_e32 v25, 0, v25, vcc
	v_max_u32_e32 v26, v18, v22
	v_max_u32_e32 v27, v19, v23
	v_max_u32_e32 v28, v20, v24
	v_max_u32_e32 v29, v21, v25
	v_max_u32_dpp v26, v26, v26 quad_perm:[1,0,3,2] row_mask:0xf bank_mask:0xf
	v_max_u32_dpp v27, v27, v27 quad_perm:[1,0,3,2] row_mask:0xf bank_mask:0xf
	v_max_u32_dpp v28, v28, v28 quad_perm:[1,0,3,2] row_mask:0xf bank_mask:0xf
	v_max_u32_dpp v29, v29, v29 quad_perm:[1,0,3,2] row_mask:0xf bank_mask:0xf
	v_max_u32_dpp v26, v26, v26 quad_perm:[2,3,0,1] row_mask:0xf bank_mask:0xf
	v_max_u32_dpp v27, v27, v27 quad_perm:[2,3,0,1] row_mask:0xf bank_mask:0xf
	v_max_u32_dpp v28, v28, v28 quad_perm:[2,3,0,1] row_mask:0xf bank_mask:0xf
	v_max_u32_dpp v29, v29, v29 quad_perm:[2,3,0,1] row_mask:0xf bank_mask:0xf
	v_max_u32_dpp v26, v26, v26 row_half_mirror row_mask:0xf bank_mask:0xf
	v_max_u32_dpp v27, v27, v27 row_half_mirror row_mask:0xf bank_mask:0xf
	v_max_u32_dpp v28, v28, v28 row_half_mirror row_mask:0xf bank_mask:0xf
	v_max_u32_dpp v29, v29, v29 row_half_mirror row_mask:0xf bank_mask:0xf
	v_max_u32_dpp v26, v26, v26 row_mirror row_mask:0xf bank_mask:0xf
	v_max_u32_dpp v27, v27, v27 row_mirror row_mask:0xf bank_mask:0xf
	v_max_u32_dpp v28, v28, v28 row_mirror row_mask:0xf bank_mask:0xf
	v_max_u32_dpp v29, v29, v29 row_mirror row_mask:0xf bank_mask:0xf
	v_max_u32_dpp v26, v26, v26 row_bcast:15 row_mask:0xa bank_mask:0xf
	v_max_u32_dpp v27, v27, v27 row_bcast:15 row_mask:0xa bank_mask:0xf
	v_max_u32_dpp v28, v28, v28 row_bcast:15 row_mask:0xa bank_mask:0xf
	v_max_u32_dpp v29, v29, v29 row_bcast:15 row_mask:0xa bank_mask:0xf
	v_max_u32_dpp v26, v26, v26 row_bcast:31 row_mask:0xc bank_mask:0xf
	v_max_u32_dpp v27, v27, v27 row_bcast:31 row_mask:0xc bank_mask:0xf
	v_max_u32_dpp v28, v28, v28 row_bcast:31 row_mask:0xc bank_mask:0xf
	v_max_u32_dpp v29, v29, v29 row_bcast:31 row_mask:0xc bank_mask:0xf
	v_readlane_b32 s14, v26, 63
	v_readlane_b32 s15, v27, 63
	v_readlane_b32 s34, v28, 63
	v_readlane_b32 s35, v29, 63
	v_writelane_b32 v82, s14, 10
	v_writelane_b32 v83, s15, 10
	v_writelane_b32 v84, s34, 10
	v_writelane_b32 v85, s35, 10
	v_cmp_ne_u32_e64 s[42:43], s14, v18
	v_cmp_ne_u32_e64 s[66:67], s14, v22
	v_cmp_ne_u32_e64 s[0:1], s15, v19
	v_cmp_ne_u32_e32 vcc, s15, v23
	v_cndmask_b32_e64 v18, 0, v18, s[42:43]
	v_cndmask_b32_e64 v22, 0, v22, s[66:67]
	v_cndmask_b32_e64 v19, 0, v19, s[0:1]
	v_cndmask_b32_e32 v23, 0, v23, vcc
	v_cmp_ne_u32_e64 s[42:43], s34, v20
	v_cmp_ne_u32_e64 s[66:67], s34, v24
	v_cmp_ne_u32_e64 s[0:1], s35, v21
	v_cmp_ne_u32_e32 vcc, s35, v25
	v_cndmask_b32_e64 v20, 0, v20, s[42:43]
	v_cndmask_b32_e64 v24, 0, v24, s[66:67]
	v_cndmask_b32_e64 v21, 0, v21, s[0:1]
	v_cndmask_b32_e32 v25, 0, v25, vcc
	v_max_u32_e32 v26, v18, v22
	v_max_u32_e32 v27, v19, v23
	v_max_u32_e32 v28, v20, v24
; __device__ __forceinline__ void nsa_quad_pre(int bg, int quad, const bf16_t* Q, const bf16_t* KV, const bf16_t* KCMP, const bf16_t* VCMPT, const float* GN, bf16_t* ONSA, ...
;     ...
;             for (int it = 0; it < 13; ++it) {
;                 unsigned m = k0 > k1 ? k0 : k1;
; #pragma unroll
;                 for (int off = 32; off >= 1; off >>= 1) { const unsigned o = (unsigned)__shfl_xor((int)m, off); m = o > m ? o : m; }
;                 if (k0 == m) k0 = 0u; if (k1 == m) k1 = 0u;
;                 if (lane == 0) selq[tt * 16 + it] = 127 - (int)(m & 127u);
;             }
;             if (lane == 0) { selq[tt * 16 + 13] = 0; selq[tt * 16 + 14] = cur - 1; selq[tt * 16 + 15] = cur; }
	v_max_u32_e32 v29, v21, v25
	v_max_u32_dpp v26, v26, v26 quad_perm:[1,0,3,2] row_mask:0xf bank_mask:0xf
	v_max_u32_dpp v27, v27, v27 quad_perm:[1,0,3,2] row_mask:0xf bank_mask:0xf
	v_max_u32_dpp v28, v28, v28 quad_perm:[1,0,3,2] row_mask:0xf bank_mask:0xf
	v_max_u32_dpp v29, v29, v29 quad_perm:[1,0,3,2] row_mask:0xf bank_mask:0xf
	v_max_u32_dpp v26, v26, v26 quad_perm:[2,3,0,1] row_mask:0xf bank_mask:0xf
	v_max_u32_dpp v27, v27, v27 quad_perm:[2,3,0,1] row_mask:0xf bank_mask:0xf
	v_max_u32_dpp v28, v28, v28 quad_perm:[2,3,0,1] row_mask:0xf bank_mask:0xf
	v_max_u32_dpp v29, v29, v29 quad_perm:[2,3,0,1] row_mask:0xf bank_mask:0xf
	v_max_u32_dpp v26, v26, v26 row_half_mirror row_mask:0xf bank_mask:0xf
	v_max_u32_dpp v27, v27, v27 row_half_mirror row_mask:0xf bank_mask:0xf
	v_max_u32_dpp v28, v28, v28 row_half_mirror row_mask:0xf bank_mask:0xf
	v_max_u32_dpp v29, v29, v29 row_half_mirror row_mask:0xf bank_mask:0xf
	v_max_u32_dpp v26, v26, v26 row_mirror row_mask:0xf bank_mask:0xf
	v_max_u32_dpp v27, v27, v27 row_mirror row_mask:0xf bank_mask:0xf
	v_max_u32_dpp v28, v28, v28 row_mirror row_mask:0xf bank_mask:0xf
	v_max_u32_dpp v29, v29, v29 row_mirror row_mask:0xf bank_mask:0xf
	v_max_u32_dpp v26, v26, v26 row_bcast:15 row_mask:0xa bank_mask:0xf
	v_max_u32_dpp v27, v27, v27 row_bcast:15 row_mask:0xa bank_mask:0xf
	v_max_u32_dpp v28, v28, v28 row_bcast:15 row_mask:0xa bank_mask:0xf
	v_max_u32_dpp v29, v29, v29 row_bcast:15 row_mask:0xa bank_mask:0xf
	v_max_u32_dpp v26, v26, v26 row_bcast:31 row_mask:0xc bank_mask:0xf
	v_max_u32_dpp v27, v27, v27 row_bcast:31 row_mask:0xc bank_mask:0xf
	v_max_u32_dpp v28, v28, v28 row_bcast:31 row_mask:0xc bank_mask:0xf
	v_max_u32_dpp v29, v29, v29 row_bcast:31 row_mask:0xc bank_mask:0xf
	v_readlane_b32 s14, v26, 63
	v_readlane_b32 s15, v27, 63
	v_readlane_b32 s34, v28, 63
	v_readlane_b32 s35, v29, 63
	v_writelane_b32 v82, s14, 11
	v_writelane_b32 v83, s15, 11
	v_writelane_b32 v84, s34, 11
	v_writelane_b32 v85, s35, 11
	v_cmp_ne_u32_e64 s[42:43], s14, v18
	v_cmp_ne_u32_e64 s[66:67], s14, v22
	v_cmp_ne_u32_e64 s[0:1], s15, v19
	v_cmp_ne_u32_e32 vcc, s15, v23
	v_cndmask_b32_e64 v18, 0, v18, s[42:43]
	v_cndmask_b32_e64 v22, 0, v22, s[66:67]
	v_cndmask_b32_e64 v19, 0, v19, s[0:1]
	v_cndmask_b32_e32 v23, 0, v23, vcc
	v_cmp_ne_u32_e64 s[42:43], s34, v20
	v_cmp_ne_u32_e64 s[66:67], s34, v24
	v_cmp_ne_u32_e64 s[0:1], s35, v21
	v_cmp_ne_u32_e32 vcc, s35, v25
	v_cndmask_b32_e64 v20, 0, v20, s[42:43]
	v_cndmask_b32_e64 v24, 0, v24, s[66:67]
	v_cndmask_b32_e64 v21, 0, v21, s[0:1]
	v_cndmask_b32_e32 v25, 0, v25, vcc
	v_max_u32_e32 v26, v18, v22
	v_max_u32_e32 v27, v19, v23
	v_max_u32_e32 v28, v20, v24
	v_max_u32_e32 v29, v21, v25
	v_max_u32_dpp v26, v26, v26 quad_perm:[1,0,3,2] row_mask:0xf bank_mask:0xf
	v_max_u32_dpp v27, v27, v27 quad_perm:[1,0,3,2] row_mask:0xf bank_mask:0xf
	v_max_u32_dpp v28, v28, v28 quad_perm:[1,0,3,2] row_mask:0xf bank_mask:0xf
	v_max_u32_dpp v29, v29, v29 quad_perm:[1,0,3,2] row_mask:0xf bank_mask:0xf
	v_max_u32_dpp v26, v26, v26 quad_perm:[2,3,0,1] row_mask:0xf bank_mask:0xf
	v_max_u32_dpp v27, v27, v27 quad_perm:[2,3,0,1] row_mask:0xf bank_mask:0xf
	v_max_u32_dpp v28, v28, v28 quad_perm:[2,3,0,1] row_mask:0xf bank_mask:0xf
	v_max_u32_dpp v29, v29, v29 quad_perm:[2,3,0,1] row_mask:0xf bank_mask:0xf
	v_max_u32_dpp v26, v26, v26 row_half_mirror row_mask:0xf bank_mask:0xf
	v_max_u32_dpp v27, v27, v27 row_half_mirror row_mask:0xf bank_mask:0xf
	v_max_u32_dpp v28, v28, v28 row_half_mirror row_mask:0xf bank_mask:0xf
	v_max_u32_dpp v29, v29, v29 row_half_mirror row_mask:0xf bank_mask:0xf
	v_max_u32_dpp v26, v26, v26 row_mirror row_mask:0xf bank_mask:0xf
	v_max_u32_dpp v27, v27, v27 row_mirror row_mask:0xf bank_mask:0xf
	v_max_u32_dpp v28, v28, v28 row_mirror row_mask:0xf bank_mask:0xf
	v_max_u32_dpp v29, v29, v29 row_mirror row_mask:0xf bank_mask:0xf
	v_max_u32_dpp v26, v26, v26 row_bcast:15 row_mask:0xa bank_mask:0xf
	v_max_u32_dpp v27, v27, v27 row_bcast:15 row_mask:0xa bank_mask:0xf
	v_max_u32_dpp v28, v28, v28 row_bcast:15 row_mask:0xa bank_mask:0xf
	v_max_u32_dpp v29, v29, v29 row_bcast:15 row_mask:0xa bank_mask:0xf
	v_max_u32_dpp v26, v26, v26 row_bcast:31 row_mask:0xc bank_mask:0xf
	v_max_u32_dpp v27, v27, v27 row_bcast:31 row_mask:0xc bank_mask:0xf
	v_max_u32_dpp v28, v28, v28 row_bcast:31 row_mask:0xc bank_mask:0xf
	v_max_u32_dpp v29, v29, v29 row_bcast:31 row_mask:0xc bank_mask:0xf
	v_readlane_b32 s14, v26, 63
	v_readlane_b32 s15, v27, 63
	v_readlane_b32 s34, v28, 63
	v_readlane_b32 s35, v29, 63
	v_writelane_b32 v82, s14, 12
	v_writelane_b32 v83, s15, 12
	v_writelane_b32 v84, s34, 12
	v_writelane_b32 v85, s35, 12
	v_and_b32_e32 v82, 127, v82
	v_sub_u32_e32 v82, 127, v82
	v_and_b32_e32 v83, 127, v83
	v_sub_u32_e32 v83, 127, v83
	v_and_b32_e32 v84, 127, v84
	v_sub_u32_e32 v84, 127, v84
	v_and_b32_e32 v85, 127, v85
	v_sub_u32_e32 v85, 127, v85
	s_add_i32 s19, s18, -1
	v_mov_b32_e32 v236, s19
	v_mov_b32_e32 v237, s18
	v_cmp_eq_u32_e64 s[14:15], 14, v184
	v_cmp_eq_u32_e64 s[34:35], 15, v184
	s_nop 0
	v_cndmask_b32_e64 v82, v82, v236, s[14:15]
	v_cndmask_b32_e64 v82, v82, v237, s[34:35]
	v_cndmask_b32_e64 v83, v83, v236, s[14:15]
	v_cndmask_b32_e64 v83, v83, v237, s[34:35]
	v_cndmask_b32_e64 v84, v84, v236, s[14:15]
	v_cndmask_b32_e64 v84, v84, v237, s[34:35]
	v_cndmask_b32_e64 v85, v85, v236, s[14:15]
	v_cndmask_b32_e64 v85, v85, v237, s[34:35]
	s_and_saveexec_b64 s[42:43], s[6:7]
	ds_write_b32 v196, v82 offset:51520
	ds_write_b32 v196, v83 offset:51584
	ds_write_b32 v196, v84 offset:51648
	ds_write_b32 v196, v85 offset:51712
	s_or_b64 exec, exec, s[42:43]
	s_branch .Ltopk_done_q1
